# v18 + P3 gated-merge epilogue: gate loads pipelined through a register ring with counted vmcnt instead of 16 serialized round trips
# baseline (speedup 1.0000x reference)
; __device__ __forceinline__ unsigned cvt_pk_bf16(float lo, float hi) { unsigned r; asm volatile("v_cvt_pk_bf16_f32 %0, %1, %2" : "=v"(r) : "v"(lo), "v"(hi)); return r; }
; __device__ __forceinline__ float sigm(float x) { return __builtin_amdgcn_rcpf(1.0f + __builtin_amdgcn_exp2f(-1.4426950408889634f * x)); }
;     __device__ __forceinline__ void operator()(f32x4 (&acc)[2][2][4][2], const Unit& u, int wr, int wc, int fr, int fq) const {
;     ...
; #pragma unroll
;             for (int ai = 0; ai < 2; ++ai)
; #pragma unroll
;                 for (int m = 0; m < 4; ++m) { const size_t off = (size_t)(row0 + ai * HALF + m * 16) * 1024 + col0;
; #pragma unroll
;                     for (int bj = 0; bj < 2; ++bj) { const u32x4 gv = *(const u32x4*)(gb + off + bj * HALF);
;                         const f32x4 v0 = acc[ai][bj][m][0], v1 = acc[ai][bj][m][1];
;                         u32x4 w; w.x = cvt_pk_bf16(v0[0] * sigm(__uint_as_float(gv.x << 16)), v0[1] * sigm(__uint_as_float(gv.x & 0xffff0000u)));
;                         w.y = cvt_pk_bf16(v0[2] * sigm(__uint_as_float(gv.y << 16)), v0[3] * sigm(__uint_as_float(gv.y & 0xffff0000u)));
;                         w.z = cvt_pk_bf16(v1[0] * sigm(__uint_as_float(gv.z << 16)), v1[1] * sigm(__uint_as_float(gv.z & 0xffff0000u)));
;                         w.w = cvt_pk_bf16(v1[2] * sigm(__uint_as_float(gv.w << 16)), v1[3] * sigm(__uint_as_float(gv.w & 0xffff0000u)));
;                         *(u32x4*)(merged + off + bj * HALF) = w; } }
.LBB0_579:
	v_lshl_add_u32 v136, s40, 8, v164
	v_lshl_or_b32 v2, s18, 8, v166
	v_ashrrev_i32_e32 v137, 31, v136
	v_ashrrev_i32_e32 v3, 31, v2
	v_lshlrev_b64 v[132:133], 10, v[136:137]
	v_lshl_add_u64 v[132:133], v[132:133], 0, v[2:3]
	v_lshlrev_b64 v[158:159], 1, v[132:133]
	v_or_b32_e32 v154, 16, v136
	v_or_b32_e32 v152, 32, v136
	v_or_b32_e32 v138, 48, v136
	s_cmp_eq_u32 s2, 0
	v_lshl_add_u64 v[156:157], s[74:75], 0, v[158:159]
	v_ashrrev_i32_e32 v155, 31, v154
	v_ashrrev_i32_e32 v153, 31, v152
	v_ashrrev_i32_e32 v139, 31, v138
	s_cbranch_scc1 .LBB0_587
	v_mov_b32_e32 v184, 0x8000
	v_mov_b32_e32 v185, 0
	v_mov_b32_e32 v186, 0x28000
	v_mov_b32_e32 v187, 0
	v_mov_b32_e32 v180, v156
	v_mov_b32_e32 v181, v157
	global_load_dwordx4 v[204:207], v[180:181], off
	global_load_dwordx4 v[208:211], v[180:181], off offset:256
	v_lshl_add_u64 v[180:181], v[180:181], 0, v[184:185]
	global_load_dwordx4 v[212:215], v[180:181], off
	global_load_dwordx4 v[216:219], v[180:181], off offset:256
	v_lshl_add_u64 v[180:181], v[180:181], 0, v[184:185]
	global_load_dwordx4 v[220:223], v[180:181], off
	global_load_dwordx4 v[224:227], v[180:181], off offset:256
	v_lshl_add_u64 v[180:181], v[180:181], 0, v[184:185]
	global_load_dwordx4 v[228:231], v[180:181], off
	global_load_dwordx4 v[232:235], v[180:181], off offset:256
	v_lshl_add_u64 v[180:181], v[180:181], 0, v[186:187]
	global_load_dwordx4 v[236:239], v[180:181], off
	global_load_dwordx4 v[240:243], v[180:181], off offset:256
	v_lshl_add_u64 v[180:181], v[180:181], 0, v[184:185]
	s_nop 0
	v_lshl_add_u64 v[160:161], s[92:93], 0, v[158:159]
	s_mov_b64 s[2:3], 0x48000
	s_waitcnt vmcnt(9)
	v_mov_b32_e32 v132, v204
	v_mov_b32_e32 v133, v205
	v_mov_b32_e32 v134, v206
	v_mov_b32_e32 v135, v207
	global_load_dwordx4 v[204:207], v[180:181], off
	v_lshlrev_b32_e32 v0, 16, v132
	v_and_b32_e32 v132, 0xffff0000, v132
	v_mul_f32_e32 v0, 0xbfb8aa3b, v0
	v_mul_f32_e32 v132, 0xbfb8aa3b, v132
	v_exp_f32_e32 v0, v0
	v_exp_f32_e32 v132, v132
	v_add_f32_e32 v0, 1.0, v0
	v_add_f32_e32 v132, 1.0, v132
	v_rcp_f32_e32 v0, v0
	v_rcp_f32_e32 v132, v132
	v_mul_f32_e32 v0, v128, v0
	v_mul_f32_e32 v132, v129, v132
	v_cvt_pk_bf16_f32 v132, v0, v132
	v_lshlrev_b32_e32 v0, 16, v133
	v_and_b32_e32 v133, 0xffff0000, v133
	v_mul_f32_e32 v0, 0xbfb8aa3b, v0
	v_mul_f32_e32 v133, 0xbfb8aa3b, v133
	v_exp_f32_e32 v0, v0
	v_exp_f32_e32 v133, v133
	v_add_f32_e32 v0, 1.0, v0
	v_add_f32_e32 v133, 1.0, v133
	v_rcp_f32_e32 v0, v0
	v_rcp_f32_e32 v133, v133
	v_mul_f32_e32 v0, v130, v0
	v_mul_f32_e32 v133, v131, v133
	v_cvt_pk_bf16_f32 v133, v0, v133
	v_lshlrev_b32_e32 v0, 16, v134
	v_and_b32_e32 v134, 0xffff0000, v134
	v_mul_f32_e32 v0, 0xbfb8aa3b, v0
	v_mul_f32_e32 v134, 0xbfb8aa3b, v134
	v_exp_f32_e32 v0, v0
	v_exp_f32_e32 v134, v134
	v_add_f32_e32 v0, 1.0, v0
	v_add_f32_e32 v134, 1.0, v134
	v_rcp_f32_e32 v0, v0
	v_rcp_f32_e32 v134, v134
	v_mul_f32_e32 v0, v124, v0
	v_mul_f32_e32 v134, v125, v134
	v_cvt_pk_bf16_f32 v134, v0, v134
	v_lshlrev_b32_e32 v0, 16, v135
	v_and_b32_e32 v135, 0xffff0000, v135
	v_mul_f32_e32 v135, 0xbfb8aa3b, v135
	v_mul_f32_e32 v0, 0xbfb8aa3b, v0
	v_exp_f32_e32 v135, v135
	v_exp_f32_e32 v0, v0
	v_add_f32_e32 v135, 1.0, v135
	v_add_f32_e32 v0, 1.0, v0
	v_rcp_f32_e32 v135, v135
	v_rcp_f32_e32 v0, v0
	v_mul_f32_e32 v135, v127, v135
	v_mul_f32_e32 v0, v126, v0
	v_cvt_pk_bf16_f32 v135, v0, v135
	global_store_dwordx4 v[160:161], v[132:135], off
	s_nop 0
	s_waitcnt vmcnt(10)
	v_mov_b32_e32 v132, v208
	v_mov_b32_e32 v133, v209
	v_mov_b32_e32 v134, v210
	v_mov_b32_e32 v135, v211
	global_load_dwordx4 v[208:211], v[180:181], off offset:256
	v_lshl_add_u64 v[180:181], v[180:181], 0, v[184:185]
	v_lshlrev_b32_e32 v0, 16, v132
	v_and_b32_e32 v132, 0xffff0000, v132
	v_mul_f32_e32 v0, 0xbfb8aa3b, v0
	v_mul_f32_e32 v132, 0xbfb8aa3b, v132
	v_exp_f32_e32 v0, v0
	v_exp_f32_e32 v132, v132
	v_add_f32_e32 v0, 1.0, v0
	v_add_f32_e32 v132, 1.0, v132
	v_rcp_f32_e32 v0, v0
	v_rcp_f32_e32 v132, v132
	v_mul_f32_e32 v0, v96, v0
	v_mul_f32_e32 v132, v97, v132
	v_cvt_pk_bf16_f32 v132, v0, v132
	v_lshlrev_b32_e32 v0, 16, v133
	v_and_b32_e32 v133, 0xffff0000, v133
	v_mul_f32_e32 v0, 0xbfb8aa3b, v0
	v_mul_f32_e32 v133, 0xbfb8aa3b, v133
	v_exp_f32_e32 v0, v0
	v_exp_f32_e32 v133, v133
	v_add_f32_e32 v0, 1.0, v0
	v_add_f32_e32 v133, 1.0, v133
	v_rcp_f32_e32 v0, v0
	v_rcp_f32_e32 v133, v133
	v_mul_f32_e32 v0, v98, v0
	v_mul_f32_e32 v133, v99, v133
	v_cvt_pk_bf16_f32 v133, v0, v133
	v_lshlrev_b32_e32 v0, 16, v134
	v_and_b32_e32 v134, 0xffff0000, v134
	v_mul_f32_e32 v0, 0xbfb8aa3b, v0
	v_mul_f32_e32 v134, 0xbfb8aa3b, v134
	v_exp_f32_e32 v0, v0
	v_exp_f32_e32 v134, v134
	v_add_f32_e32 v0, 1.0, v0
	v_add_f32_e32 v134, 1.0, v134
	v_rcp_f32_e32 v0, v0
	v_rcp_f32_e32 v134, v134
	v_mul_f32_e32 v0, v92, v0
	v_mul_f32_e32 v134, v93, v134
	v_cvt_pk_bf16_f32 v134, v0, v134
	v_lshlrev_b32_e32 v0, 16, v135
	v_and_b32_e32 v135, 0xffff0000, v135
	v_mul_f32_e32 v135, 0xbfb8aa3b, v135
	v_mul_f32_e32 v0, 0xbfb8aa3b, v0
	v_exp_f32_e32 v135, v135
	v_exp_f32_e32 v0, v0
	v_add_f32_e32 v135, 1.0, v135
	v_add_f32_e32 v0, 1.0, v0
	v_rcp_f32_e32 v135, v135
	v_rcp_f32_e32 v0, v0
	v_mul_f32_e32 v135, v95, v135
	v_mul_f32_e32 v0, v94, v0
	v_cvt_pk_bf16_f32 v135, v0, v135
	global_store_dwordx4 v[160:161], v[132:135], off offset:256
	s_nop 1
	v_lshlrev_b64 v[132:133], 10, v[154:155]
	v_lshl_add_u64 v[132:133], v[132:133], 0, v[2:3]
	v_lshlrev_b64 v[162:163], 1, v[132:133]
	v_lshl_add_u64 v[160:161], s[74:75], 0, v[162:163]
	s_nop 0
	v_lshl_add_u64 v[162:163], s[92:93], 0, v[162:163]
	s_waitcnt vmcnt(11)
; __device__ __forceinline__ unsigned cvt_pk_bf16(float lo, float hi) { unsigned r; asm volatile("v_cvt_pk_bf16_f32 %0, %1, %2" : "=v"(r) : "v"(lo), "v"(hi)); return r; }
; __device__ __forceinline__ float sigm(float x) { return __builtin_amdgcn_rcpf(1.0f + __builtin_amdgcn_exp2f(-1.4426950408889634f * x)); }
;     __device__ __forceinline__ void operator()(f32x4 (&acc)[2][2][4][2], const Unit& u, int wr, int wc, int fr, int fq) const {
;     ...
; #pragma unroll
;             for (int ai = 0; ai < 2; ++ai)
; #pragma unroll
;                 for (int m = 0; m < 4; ++m) { const size_t off = (size_t)(row0 + ai * HALF + m * 16) * 1024 + col0;
; #pragma unroll
;                     for (int bj = 0; bj < 2; ++bj) { const u32x4 gv = *(const u32x4*)(gb + off + bj * HALF);
;                         const f32x4 v0 = acc[ai][bj][m][0], v1 = acc[ai][bj][m][1];
;                         u32x4 w; w.x = cvt_pk_bf16(v0[0] * sigm(__uint_as_float(gv.x << 16)), v0[1] * sigm(__uint_as_float(gv.x & 0xffff0000u)));
;                         w.y = cvt_pk_bf16(v0[2] * sigm(__uint_as_float(gv.y << 16)), v0[3] * sigm(__uint_as_float(gv.y & 0xffff0000u)));
;                         w.z = cvt_pk_bf16(v1[0] * sigm(__uint_as_float(gv.z << 16)), v1[1] * sigm(__uint_as_float(gv.z & 0xffff0000u)));
;                         w.w = cvt_pk_bf16(v1[2] * sigm(__uint_as_float(gv.w << 16)), v1[3] * sigm(__uint_as_float(gv.w & 0xffff0000u)));
;                         *(u32x4*)(merged + off + bj * HALF) = w; } }
	v_mov_b32_e32 v132, v212
	v_mov_b32_e32 v133, v213
	v_mov_b32_e32 v134, v214
	v_mov_b32_e32 v135, v215
	global_load_dwordx4 v[212:215], v[180:181], off
	v_lshlrev_b32_e32 v0, 16, v132
	v_and_b32_e32 v132, 0xffff0000, v132
	v_mul_f32_e32 v0, 0xbfb8aa3b, v0
	v_mul_f32_e32 v132, 0xbfb8aa3b, v132
	v_exp_f32_e32 v0, v0
	v_exp_f32_e32 v132, v132
	v_add_f32_e32 v0, 1.0, v0
	v_add_f32_e32 v132, 1.0, v132
	v_rcp_f32_e32 v0, v0
	v_rcp_f32_e32 v132, v132
	v_mul_f32_e32 v0, v120, v0
	v_mul_f32_e32 v132, v121, v132
	v_cvt_pk_bf16_f32 v132, v0, v132
	v_lshlrev_b32_e32 v0, 16, v133
	v_and_b32_e32 v133, 0xffff0000, v133
	v_mul_f32_e32 v0, 0xbfb8aa3b, v0
	v_mul_f32_e32 v133, 0xbfb8aa3b, v133
	v_exp_f32_e32 v0, v0
	v_exp_f32_e32 v133, v133
	v_add_f32_e32 v0, 1.0, v0
	v_add_f32_e32 v133, 1.0, v133
	v_rcp_f32_e32 v0, v0
	v_rcp_f32_e32 v133, v133
	v_mul_f32_e32 v0, v122, v0
	v_mul_f32_e32 v133, v123, v133
	v_cvt_pk_bf16_f32 v133, v0, v133
	v_lshlrev_b32_e32 v0, 16, v134
	v_and_b32_e32 v134, 0xffff0000, v134
	v_mul_f32_e32 v0, 0xbfb8aa3b, v0
	v_mul_f32_e32 v134, 0xbfb8aa3b, v134
	v_exp_f32_e32 v0, v0
	v_exp_f32_e32 v134, v134
	v_add_f32_e32 v0, 1.0, v0
	v_add_f32_e32 v134, 1.0, v134
	v_rcp_f32_e32 v0, v0
	v_rcp_f32_e32 v134, v134
	v_mul_f32_e32 v0, v116, v0
	v_mul_f32_e32 v134, v117, v134
	v_cvt_pk_bf16_f32 v134, v0, v134
	v_lshlrev_b32_e32 v0, 16, v135
	v_and_b32_e32 v135, 0xffff0000, v135
	v_mul_f32_e32 v135, 0xbfb8aa3b, v135
	v_mul_f32_e32 v0, 0xbfb8aa3b, v0
	v_exp_f32_e32 v135, v135
	v_exp_f32_e32 v0, v0
	v_add_f32_e32 v135, 1.0, v135
	v_add_f32_e32 v0, 1.0, v0
	v_rcp_f32_e32 v135, v135
	v_rcp_f32_e32 v0, v0
	v_mul_f32_e32 v135, v119, v135
	v_mul_f32_e32 v0, v118, v0
	v_cvt_pk_bf16_f32 v135, v0, v135
	global_store_dwordx4 v[162:163], v[132:135], off
	s_nop 0
	s_waitcnt vmcnt(12)
	v_mov_b32_e32 v132, v216
	v_mov_b32_e32 v133, v217
	v_mov_b32_e32 v134, v218
	v_mov_b32_e32 v135, v219
	global_load_dwordx4 v[216:219], v[180:181], off offset:256
	v_lshl_add_u64 v[180:181], v[180:181], 0, v[184:185]
	v_lshlrev_b32_e32 v0, 16, v132
	v_and_b32_e32 v132, 0xffff0000, v132
	v_mul_f32_e32 v0, 0xbfb8aa3b, v0
	v_mul_f32_e32 v132, 0xbfb8aa3b, v132
	v_exp_f32_e32 v0, v0
	v_exp_f32_e32 v132, v132
	v_add_f32_e32 v0, 1.0, v0
	v_add_f32_e32 v132, 1.0, v132
	v_rcp_f32_e32 v0, v0
	v_rcp_f32_e32 v132, v132
	v_mul_f32_e32 v0, v88, v0
	v_mul_f32_e32 v132, v89, v132
	v_cvt_pk_bf16_f32 v132, v0, v132
	v_lshlrev_b32_e32 v0, 16, v133
	v_and_b32_e32 v133, 0xffff0000, v133
	v_mul_f32_e32 v0, 0xbfb8aa3b, v0
	v_mul_f32_e32 v133, 0xbfb8aa3b, v133
	v_exp_f32_e32 v0, v0
	v_exp_f32_e32 v133, v133
	v_add_f32_e32 v0, 1.0, v0
	v_add_f32_e32 v133, 1.0, v133
	v_rcp_f32_e32 v0, v0
	v_rcp_f32_e32 v133, v133
	v_mul_f32_e32 v0, v90, v0
	v_mul_f32_e32 v133, v91, v133
	v_cvt_pk_bf16_f32 v133, v0, v133
	v_lshlrev_b32_e32 v0, 16, v134
	v_and_b32_e32 v134, 0xffff0000, v134
	v_mul_f32_e32 v0, 0xbfb8aa3b, v0
	v_mul_f32_e32 v134, 0xbfb8aa3b, v134
	v_exp_f32_e32 v0, v0
	v_exp_f32_e32 v134, v134
	v_add_f32_e32 v0, 1.0, v0
	v_add_f32_e32 v134, 1.0, v134
	v_rcp_f32_e32 v0, v0
	v_rcp_f32_e32 v134, v134
	v_mul_f32_e32 v0, v84, v0
	v_mul_f32_e32 v134, v85, v134
	v_cvt_pk_bf16_f32 v134, v0, v134
	v_lshlrev_b32_e32 v0, 16, v135
	v_and_b32_e32 v135, 0xffff0000, v135
	v_mul_f32_e32 v135, 0xbfb8aa3b, v135
	v_mul_f32_e32 v0, 0xbfb8aa3b, v0
	v_exp_f32_e32 v135, v135
	v_exp_f32_e32 v0, v0
	v_add_f32_e32 v135, 1.0, v135
	v_add_f32_e32 v0, 1.0, v0
	v_rcp_f32_e32 v135, v135
	v_rcp_f32_e32 v0, v0
	v_mul_f32_e32 v135, v87, v135
	v_mul_f32_e32 v0, v86, v0
	v_cvt_pk_bf16_f32 v135, v0, v135
	global_store_dwordx4 v[162:163], v[132:135], off offset:256
	s_nop 1
	v_lshlrev_b64 v[132:133], 10, v[152:153]
	v_lshl_add_u64 v[132:133], v[132:133], 0, v[2:3]
	v_lshlrev_b64 v[162:163], 1, v[132:133]
	v_lshl_add_u64 v[160:161], s[74:75], 0, v[162:163]
	s_nop 0
	v_lshl_add_u64 v[162:163], s[92:93], 0, v[162:163]
	s_waitcnt vmcnt(13)
	v_mov_b32_e32 v132, v220
	v_mov_b32_e32 v133, v221
	v_mov_b32_e32 v134, v222
	v_mov_b32_e32 v135, v223
	global_load_dwordx4 v[220:223], v[180:181], off
	v_lshlrev_b32_e32 v0, 16, v132
	v_and_b32_e32 v132, 0xffff0000, v132
	v_mul_f32_e32 v0, 0xbfb8aa3b, v0
	v_mul_f32_e32 v132, 0xbfb8aa3b, v132
	v_exp_f32_e32 v0, v0
	v_exp_f32_e32 v132, v132
	v_add_f32_e32 v0, 1.0, v0
	v_add_f32_e32 v132, 1.0, v132
	v_rcp_f32_e32 v0, v0
	v_rcp_f32_e32 v132, v132
	v_mul_f32_e32 v0, v112, v0
	v_mul_f32_e32 v132, v113, v132
	v_cvt_pk_bf16_f32 v132, v0, v132
	v_lshlrev_b32_e32 v0, 16, v133
	v_and_b32_e32 v133, 0xffff0000, v133
	v_mul_f32_e32 v0, 0xbfb8aa3b, v0
	v_mul_f32_e32 v133, 0xbfb8aa3b, v133
	v_exp_f32_e32 v0, v0
	v_exp_f32_e32 v133, v133
	v_add_f32_e32 v0, 1.0, v0
	v_add_f32_e32 v133, 1.0, v133
	v_rcp_f32_e32 v0, v0
	v_rcp_f32_e32 v133, v133
	v_mul_f32_e32 v0, v114, v0
	v_mul_f32_e32 v133, v115, v133
	v_cvt_pk_bf16_f32 v133, v0, v133
	v_lshlrev_b32_e32 v0, 16, v134
	v_and_b32_e32 v134, 0xffff0000, v134
	v_mul_f32_e32 v0, 0xbfb8aa3b, v0
	v_mul_f32_e32 v134, 0xbfb8aa3b, v134
	v_exp_f32_e32 v0, v0
	v_exp_f32_e32 v134, v134
	v_add_f32_e32 v0, 1.0, v0
	v_add_f32_e32 v134, 1.0, v134
	v_rcp_f32_e32 v0, v0
	v_rcp_f32_e32 v134, v134
	v_mul_f32_e32 v0, v108, v0
	v_mul_f32_e32 v134, v109, v134
	v_cvt_pk_bf16_f32 v134, v0, v134
	v_lshlrev_b32_e32 v0, 16, v135
	v_and_b32_e32 v135, 0xffff0000, v135
	v_mul_f32_e32 v135, 0xbfb8aa3b, v135
	v_mul_f32_e32 v0, 0xbfb8aa3b, v0
	v_exp_f32_e32 v135, v135
	v_exp_f32_e32 v0, v0
	v_add_f32_e32 v135, 1.0, v135
	v_add_f32_e32 v0, 1.0, v0
	v_rcp_f32_e32 v135, v135
	v_rcp_f32_e32 v0, v0
	v_mul_f32_e32 v135, v111, v135
	v_mul_f32_e32 v0, v110, v0
	v_cvt_pk_bf16_f32 v135, v0, v135
	global_store_dwordx4 v[162:163], v[132:135], off
	s_nop 0
	s_waitcnt vmcnt(14)
; __device__ __forceinline__ unsigned cvt_pk_bf16(float lo, float hi) { unsigned r; asm volatile("v_cvt_pk_bf16_f32 %0, %1, %2" : "=v"(r) : "v"(lo), "v"(hi)); return r; }
; __device__ __forceinline__ float sigm(float x) { return __builtin_amdgcn_rcpf(1.0f + __builtin_amdgcn_exp2f(-1.4426950408889634f * x)); }
;     __device__ __forceinline__ void operator()(f32x4 (&acc)[2][2][4][2], const Unit& u, int wr, int wc, int fr, int fq) const {
;     ...
; #pragma unroll
;             for (int ai = 0; ai < 2; ++ai)
; #pragma unroll
;                 for (int m = 0; m < 4; ++m) { const size_t off = (size_t)(row0 + ai * HALF + m * 16) * 1024 + col0;
; #pragma unroll
;                     for (int bj = 0; bj < 2; ++bj) { const u32x4 gv = *(const u32x4*)(gb + off + bj * HALF);
;                         const f32x4 v0 = acc[ai][bj][m][0], v1 = acc[ai][bj][m][1];
;                         u32x4 w; w.x = cvt_pk_bf16(v0[0] * sigm(__uint_as_float(gv.x << 16)), v0[1] * sigm(__uint_as_float(gv.x & 0xffff0000u)));
;                         w.y = cvt_pk_bf16(v0[2] * sigm(__uint_as_float(gv.y << 16)), v0[3] * sigm(__uint_as_float(gv.y & 0xffff0000u)));
;                         w.z = cvt_pk_bf16(v1[0] * sigm(__uint_as_float(gv.z << 16)), v1[1] * sigm(__uint_as_float(gv.z & 0xffff0000u)));
;                         w.w = cvt_pk_bf16(v1[2] * sigm(__uint_as_float(gv.w << 16)), v1[3] * sigm(__uint_as_float(gv.w & 0xffff0000u)));
;                         *(u32x4*)(merged + off + bj * HALF) = w; } }
	v_mov_b32_e32 v132, v224
	v_mov_b32_e32 v133, v225
	v_mov_b32_e32 v134, v226
	v_mov_b32_e32 v135, v227
	global_load_dwordx4 v[224:227], v[180:181], off offset:256
	v_lshlrev_b32_e32 v0, 16, v132
	v_and_b32_e32 v132, 0xffff0000, v132
	v_mul_f32_e32 v0, 0xbfb8aa3b, v0
	v_mul_f32_e32 v132, 0xbfb8aa3b, v132
	v_exp_f32_e32 v0, v0
	v_exp_f32_e32 v132, v132
	v_add_f32_e32 v0, 1.0, v0
	v_add_f32_e32 v132, 1.0, v132
	v_rcp_f32_e32 v0, v0
	v_rcp_f32_e32 v132, v132
	v_mul_f32_e32 v0, v80, v0
	v_mul_f32_e32 v132, v81, v132
	v_cvt_pk_bf16_f32 v132, v0, v132
	v_lshlrev_b32_e32 v0, 16, v133
	v_and_b32_e32 v133, 0xffff0000, v133
	v_mul_f32_e32 v0, 0xbfb8aa3b, v0
	v_mul_f32_e32 v133, 0xbfb8aa3b, v133
	v_exp_f32_e32 v0, v0
	v_exp_f32_e32 v133, v133
	v_add_f32_e32 v0, 1.0, v0
	v_add_f32_e32 v133, 1.0, v133
	v_rcp_f32_e32 v0, v0
	v_rcp_f32_e32 v133, v133
	v_mul_f32_e32 v0, v82, v0
	v_mul_f32_e32 v133, v83, v133
	v_cvt_pk_bf16_f32 v133, v0, v133
	v_lshlrev_b32_e32 v0, 16, v134
	v_and_b32_e32 v134, 0xffff0000, v134
	v_mul_f32_e32 v0, 0xbfb8aa3b, v0
	v_mul_f32_e32 v134, 0xbfb8aa3b, v134
	v_exp_f32_e32 v0, v0
	v_exp_f32_e32 v134, v134
	v_add_f32_e32 v0, 1.0, v0
	v_add_f32_e32 v134, 1.0, v134
	v_rcp_f32_e32 v0, v0
	v_rcp_f32_e32 v134, v134
	v_mul_f32_e32 v0, v76, v0
	v_mul_f32_e32 v134, v77, v134
	v_cvt_pk_bf16_f32 v134, v0, v134
	v_lshlrev_b32_e32 v0, 16, v135
	v_and_b32_e32 v135, 0xffff0000, v135
	v_mul_f32_e32 v135, 0xbfb8aa3b, v135
	v_mul_f32_e32 v0, 0xbfb8aa3b, v0
	v_exp_f32_e32 v135, v135
	v_exp_f32_e32 v0, v0
	v_add_f32_e32 v135, 1.0, v135
	v_add_f32_e32 v0, 1.0, v0
	v_rcp_f32_e32 v135, v135
	v_rcp_f32_e32 v0, v0
	v_mul_f32_e32 v135, v79, v135
	v_mul_f32_e32 v0, v78, v0
	v_cvt_pk_bf16_f32 v135, v0, v135
	global_store_dwordx4 v[162:163], v[132:135], off offset:256
	s_nop 1
	v_lshlrev_b64 v[132:133], 10, v[138:139]
	v_lshl_add_u64 v[132:133], v[132:133], 0, v[2:3]
	v_lshlrev_b64 v[162:163], 1, v[132:133]
	v_lshl_add_u64 v[160:161], s[74:75], 0, v[162:163]
	s_nop 0
	v_lshl_add_u64 v[162:163], s[92:93], 0, v[162:163]
	s_waitcnt vmcnt(15)
	v_mov_b32_e32 v132, v228
	v_mov_b32_e32 v133, v229
	v_mov_b32_e32 v134, v230
	v_mov_b32_e32 v135, v231
	v_lshlrev_b32_e32 v0, 16, v132
	v_and_b32_e32 v132, 0xffff0000, v132
	v_mul_f32_e32 v0, 0xbfb8aa3b, v0
	v_mul_f32_e32 v132, 0xbfb8aa3b, v132
	v_exp_f32_e32 v0, v0
	v_exp_f32_e32 v132, v132
	v_add_f32_e32 v0, 1.0, v0
	v_add_f32_e32 v132, 1.0, v132
	v_rcp_f32_e32 v0, v0
	v_rcp_f32_e32 v132, v132
	v_mul_f32_e32 v0, v104, v0
	v_mul_f32_e32 v132, v105, v132
	v_cvt_pk_bf16_f32 v132, v0, v132
	v_lshlrev_b32_e32 v0, 16, v133
	v_and_b32_e32 v133, 0xffff0000, v133
	v_mul_f32_e32 v0, 0xbfb8aa3b, v0
	v_mul_f32_e32 v133, 0xbfb8aa3b, v133
	v_exp_f32_e32 v0, v0
	v_exp_f32_e32 v133, v133
	v_add_f32_e32 v0, 1.0, v0
	v_add_f32_e32 v133, 1.0, v133
	v_rcp_f32_e32 v0, v0
	v_rcp_f32_e32 v133, v133
	v_mul_f32_e32 v0, v106, v0
	v_mul_f32_e32 v133, v107, v133
	v_cvt_pk_bf16_f32 v133, v0, v133
	v_lshlrev_b32_e32 v0, 16, v134
	v_and_b32_e32 v134, 0xffff0000, v134
	v_mul_f32_e32 v0, 0xbfb8aa3b, v0
	v_mul_f32_e32 v134, 0xbfb8aa3b, v134
	v_exp_f32_e32 v0, v0
	v_exp_f32_e32 v134, v134
	v_add_f32_e32 v0, 1.0, v0
	v_add_f32_e32 v134, 1.0, v134
	v_rcp_f32_e32 v0, v0
	v_rcp_f32_e32 v134, v134
	v_mul_f32_e32 v0, v100, v0
	v_mul_f32_e32 v134, v101, v134
	v_cvt_pk_bf16_f32 v134, v0, v134
	v_lshlrev_b32_e32 v0, 16, v135
	v_and_b32_e32 v135, 0xffff0000, v135
	v_mul_f32_e32 v135, 0xbfb8aa3b, v135
	v_mul_f32_e32 v0, 0xbfb8aa3b, v0
	v_exp_f32_e32 v135, v135
	v_exp_f32_e32 v0, v0
	v_add_f32_e32 v135, 1.0, v135
	v_add_f32_e32 v0, 1.0, v0
	v_rcp_f32_e32 v135, v135
	v_rcp_f32_e32 v0, v0
	v_mul_f32_e32 v135, v103, v135
	v_mul_f32_e32 v0, v102, v0
	v_cvt_pk_bf16_f32 v135, v0, v135
	global_store_dwordx4 v[162:163], v[132:135], off
	s_nop 0
	s_waitcnt vmcnt(15)
	v_mov_b32_e32 v132, v232
	v_mov_b32_e32 v133, v233
	v_mov_b32_e32 v134, v234
	v_mov_b32_e32 v135, v235
	v_lshlrev_b32_e32 v0, 16, v132
	v_and_b32_e32 v132, 0xffff0000, v132
	v_mul_f32_e32 v0, 0xbfb8aa3b, v0
	v_mul_f32_e32 v132, 0xbfb8aa3b, v132
	v_exp_f32_e32 v0, v0
	v_exp_f32_e32 v132, v132
	v_add_f32_e32 v0, 1.0, v0
	v_add_f32_e32 v132, 1.0, v132
	v_rcp_f32_e32 v0, v0
	v_rcp_f32_e32 v132, v132
	v_mul_f32_e32 v0, v72, v0
	v_mul_f32_e32 v132, v73, v132
	v_cvt_pk_bf16_f32 v132, v0, v132
	v_lshlrev_b32_e32 v0, 16, v133
	v_and_b32_e32 v133, 0xffff0000, v133
	v_mul_f32_e32 v0, 0xbfb8aa3b, v0
	v_mul_f32_e32 v133, 0xbfb8aa3b, v133
	v_exp_f32_e32 v0, v0
	v_exp_f32_e32 v133, v133
	v_add_f32_e32 v0, 1.0, v0
	v_add_f32_e32 v133, 1.0, v133
	v_rcp_f32_e32 v0, v0
	v_rcp_f32_e32 v133, v133
	v_mul_f32_e32 v0, v74, v0
	v_mul_f32_e32 v133, v75, v133
	v_cvt_pk_bf16_f32 v133, v0, v133
	v_lshlrev_b32_e32 v0, 16, v134
	v_and_b32_e32 v134, 0xffff0000, v134
	v_mul_f32_e32 v0, 0xbfb8aa3b, v0
	v_mul_f32_e32 v134, 0xbfb8aa3b, v134
	v_exp_f32_e32 v0, v0
	v_exp_f32_e32 v134, v134
	v_add_f32_e32 v0, 1.0, v0
	v_add_f32_e32 v134, 1.0, v134
	v_rcp_f32_e32 v0, v0
	v_rcp_f32_e32 v134, v134
	v_mul_f32_e32 v0, v68, v0
	v_mul_f32_e32 v134, v69, v134
	v_cvt_pk_bf16_f32 v134, v0, v134
	v_lshlrev_b32_e32 v0, 16, v135
	v_and_b32_e32 v135, 0xffff0000, v135
	v_mul_f32_e32 v135, 0xbfb8aa3b, v135
	v_mul_f32_e32 v0, 0xbfb8aa3b, v0
	v_exp_f32_e32 v135, v135
	v_exp_f32_e32 v0, v0
	v_add_f32_e32 v135, 1.0, v135
	v_add_f32_e32 v0, 1.0, v0
	v_rcp_f32_e32 v135, v135
	v_rcp_f32_e32 v0, v0
	v_mul_f32_e32 v135, v71, v135
	v_mul_f32_e32 v0, v70, v0
	v_cvt_pk_bf16_f32 v135, v0, v135
	global_store_dwordx4 v[162:163], v[132:135], off offset:256
	v_lshl_add_u64 v[162:163], v[158:159], 0, s[54:55]
	v_lshl_add_u64 v[160:161], s[74:75], 0, v[162:163]
	s_nop 0
	v_lshl_add_u64 v[162:163], s[92:93], 0, v[162:163]
	s_waitcnt vmcnt(15)
; __device__ __forceinline__ unsigned cvt_pk_bf16(float lo, float hi) { unsigned r; asm volatile("v_cvt_pk_bf16_f32 %0, %1, %2" : "=v"(r) : "v"(lo), "v"(hi)); return r; }
; __device__ __forceinline__ float sigm(float x) { return __builtin_amdgcn_rcpf(1.0f + __builtin_amdgcn_exp2f(-1.4426950408889634f * x)); }
;     __device__ __forceinline__ void operator()(f32x4 (&acc)[2][2][4][2], const Unit& u, int wr, int wc, int fr, int fq) const {
;     ...
;                     for (int bj = 0; bj < 2; ++bj) { const u32x4 gv = *(const u32x4*)(gb + off + bj * HALF);
;                         const f32x4 v0 = acc[ai][bj][m][0], v1 = acc[ai][bj][m][1];
;                         u32x4 w; w.x = cvt_pk_bf16(v0[0] * sigm(__uint_as_float(gv.x << 16)), v0[1] * sigm(__uint_as_float(gv.x & 0xffff0000u)));
;                         w.y = cvt_pk_bf16(v0[2] * sigm(__uint_as_float(gv.y << 16)), v0[3] * sigm(__uint_as_float(gv.y & 0xffff0000u)));
;                         w.z = cvt_pk_bf16(v1[0] * sigm(__uint_as_float(gv.z << 16)), v1[1] * sigm(__uint_as_float(gv.z & 0xffff0000u)));
;                         w.w = cvt_pk_bf16(v1[2] * sigm(__uint_as_float(gv.w << 16)), v1[3] * sigm(__uint_as_float(gv.w & 0xffff0000u)));
;                         *(u32x4*)(merged + off + bj * HALF) = w; } }
	v_mov_b32_e32 v132, v236
	v_mov_b32_e32 v133, v237
	v_mov_b32_e32 v134, v238
	v_mov_b32_e32 v135, v239
	v_lshlrev_b32_e32 v0, 16, v132
	v_and_b32_e32 v132, 0xffff0000, v132
	v_mul_f32_e32 v0, 0xbfb8aa3b, v0
	v_mul_f32_e32 v132, 0xbfb8aa3b, v132
	v_exp_f32_e32 v0, v0
	v_exp_f32_e32 v132, v132
	v_add_f32_e32 v0, 1.0, v0
	v_add_f32_e32 v132, 1.0, v132
	v_rcp_f32_e32 v0, v0
	v_rcp_f32_e32 v132, v132
	v_mul_f32_e32 v0, v64, v0
	v_mul_f32_e32 v132, v65, v132
	v_cvt_pk_bf16_f32 v132, v0, v132
	v_lshlrev_b32_e32 v0, 16, v133
	v_and_b32_e32 v133, 0xffff0000, v133
	v_mul_f32_e32 v0, 0xbfb8aa3b, v0
	v_mul_f32_e32 v133, 0xbfb8aa3b, v133
	v_exp_f32_e32 v0, v0
	v_exp_f32_e32 v133, v133
	v_add_f32_e32 v0, 1.0, v0
	v_add_f32_e32 v133, 1.0, v133
	v_rcp_f32_e32 v0, v0
	v_rcp_f32_e32 v133, v133
	v_mul_f32_e32 v0, v66, v0
	v_mul_f32_e32 v133, v67, v133
	v_cvt_pk_bf16_f32 v133, v0, v133
	v_lshlrev_b32_e32 v0, 16, v134
	v_and_b32_e32 v134, 0xffff0000, v134
	v_mul_f32_e32 v0, 0xbfb8aa3b, v0
	v_mul_f32_e32 v134, 0xbfb8aa3b, v134
	v_exp_f32_e32 v0, v0
	v_exp_f32_e32 v134, v134
	v_add_f32_e32 v0, 1.0, v0
	v_add_f32_e32 v134, 1.0, v134
	v_rcp_f32_e32 v0, v0
	v_rcp_f32_e32 v134, v134
	v_mul_f32_e32 v0, v60, v0
	v_mul_f32_e32 v134, v61, v134
	v_cvt_pk_bf16_f32 v134, v0, v134
	v_lshlrev_b32_e32 v0, 16, v135
	v_and_b32_e32 v135, 0xffff0000, v135
	v_mul_f32_e32 v135, 0xbfb8aa3b, v135
	v_mul_f32_e32 v0, 0xbfb8aa3b, v0
	v_exp_f32_e32 v135, v135
	v_exp_f32_e32 v0, v0
	v_add_f32_e32 v135, 1.0, v135
	v_add_f32_e32 v0, 1.0, v0
	v_rcp_f32_e32 v135, v135
	v_rcp_f32_e32 v0, v0
	v_mul_f32_e32 v135, v63, v135
	v_mul_f32_e32 v0, v62, v0
	v_cvt_pk_bf16_f32 v135, v0, v135
	global_store_dwordx4 v[162:163], v[132:135], off
	s_nop 0
	s_waitcnt vmcnt(15)
	v_mov_b32_e32 v132, v240
	v_mov_b32_e32 v133, v241
	v_mov_b32_e32 v134, v242
	v_mov_b32_e32 v135, v243
	v_lshlrev_b32_e32 v0, 16, v132
	v_and_b32_e32 v132, 0xffff0000, v132
	v_mul_f32_e32 v0, 0xbfb8aa3b, v0
	v_mul_f32_e32 v132, 0xbfb8aa3b, v132
	v_exp_f32_e32 v0, v0
	v_exp_f32_e32 v132, v132
	v_add_f32_e32 v0, 1.0, v0
	v_add_f32_e32 v132, 1.0, v132
	v_rcp_f32_e32 v0, v0
	v_rcp_f32_e32 v132, v132
	v_mul_f32_e32 v0, v32, v0
	v_mul_f32_e32 v132, v33, v132
	v_cvt_pk_bf16_f32 v132, v0, v132
	v_lshlrev_b32_e32 v0, 16, v133
	v_and_b32_e32 v133, 0xffff0000, v133
	v_mul_f32_e32 v0, 0xbfb8aa3b, v0
	v_mul_f32_e32 v133, 0xbfb8aa3b, v133
	v_exp_f32_e32 v0, v0
	v_exp_f32_e32 v133, v133
	v_add_f32_e32 v0, 1.0, v0
	v_add_f32_e32 v133, 1.0, v133
	v_rcp_f32_e32 v0, v0
	v_rcp_f32_e32 v133, v133
	v_mul_f32_e32 v0, v34, v0
	v_mul_f32_e32 v133, v35, v133
	v_cvt_pk_bf16_f32 v133, v0, v133
	v_lshlrev_b32_e32 v0, 16, v134
	v_and_b32_e32 v134, 0xffff0000, v134
	v_mul_f32_e32 v0, 0xbfb8aa3b, v0
	v_mul_f32_e32 v134, 0xbfb8aa3b, v134
	v_exp_f32_e32 v0, v0
	v_exp_f32_e32 v134, v134
	v_add_f32_e32 v0, 1.0, v0
	v_add_f32_e32 v134, 1.0, v134
	v_rcp_f32_e32 v0, v0
	v_rcp_f32_e32 v134, v134
	v_mul_f32_e32 v0, v28, v0
	v_mul_f32_e32 v134, v29, v134
	v_cvt_pk_bf16_f32 v134, v0, v134
	v_lshlrev_b32_e32 v0, 16, v135
	v_and_b32_e32 v135, 0xffff0000, v135
	v_mul_f32_e32 v135, 0xbfb8aa3b, v135
	v_mul_f32_e32 v0, 0xbfb8aa3b, v0
	v_exp_f32_e32 v135, v135
	v_exp_f32_e32 v0, v0
	v_add_f32_e32 v135, 1.0, v135
	v_add_f32_e32 v0, 1.0, v0
	v_rcp_f32_e32 v135, v135
	v_rcp_f32_e32 v0, v0
	v_mul_f32_e32 v135, v31, v135
	v_mul_f32_e32 v0, v30, v0
	v_cvt_pk_bf16_f32 v135, v0, v135
	global_store_dwordx4 v[162:163], v[132:135], off offset:256
	v_lshl_add_u64 v[162:163], v[158:159], 0, s[2:3]
	v_lshl_add_u64 v[160:161], s[74:75], 0, v[162:163]
	s_nop 0
	v_lshl_add_u64 v[162:163], s[92:93], 0, v[162:163]
	s_mov_b64 s[2:3], 0x50000
	s_waitcnt vmcnt(15)
	v_mov_b32_e32 v132, v204
	v_mov_b32_e32 v133, v205
	v_mov_b32_e32 v134, v206
	v_mov_b32_e32 v135, v207
	v_lshlrev_b32_e32 v0, 16, v132
	v_and_b32_e32 v132, 0xffff0000, v132
	v_mul_f32_e32 v0, 0xbfb8aa3b, v0
	v_mul_f32_e32 v132, 0xbfb8aa3b, v132
	v_exp_f32_e32 v0, v0
	v_exp_f32_e32 v132, v132
	v_add_f32_e32 v0, 1.0, v0
	v_add_f32_e32 v132, 1.0, v132
	v_rcp_f32_e32 v0, v0
	v_rcp_f32_e32 v132, v132
	v_mul_f32_e32 v0, v56, v0
	v_mul_f32_e32 v132, v57, v132
	v_cvt_pk_bf16_f32 v132, v0, v132
	v_lshlrev_b32_e32 v0, 16, v133
	v_and_b32_e32 v133, 0xffff0000, v133
	v_mul_f32_e32 v0, 0xbfb8aa3b, v0
	v_mul_f32_e32 v133, 0xbfb8aa3b, v133
	v_exp_f32_e32 v0, v0
	v_exp_f32_e32 v133, v133
	v_add_f32_e32 v0, 1.0, v0
	v_add_f32_e32 v133, 1.0, v133
	v_rcp_f32_e32 v0, v0
	v_rcp_f32_e32 v133, v133
	v_mul_f32_e32 v0, v58, v0
	v_mul_f32_e32 v133, v59, v133
	v_cvt_pk_bf16_f32 v133, v0, v133
	v_lshlrev_b32_e32 v0, 16, v134
	v_and_b32_e32 v134, 0xffff0000, v134
	v_mul_f32_e32 v0, 0xbfb8aa3b, v0
	v_mul_f32_e32 v134, 0xbfb8aa3b, v134
	v_exp_f32_e32 v0, v0
	v_exp_f32_e32 v134, v134
	v_add_f32_e32 v0, 1.0, v0
	v_add_f32_e32 v134, 1.0, v134
	v_rcp_f32_e32 v0, v0
	v_rcp_f32_e32 v134, v134
	v_mul_f32_e32 v0, v52, v0
	v_mul_f32_e32 v134, v53, v134
	v_cvt_pk_bf16_f32 v134, v0, v134
	v_lshlrev_b32_e32 v0, 16, v135
	v_and_b32_e32 v135, 0xffff0000, v135
	v_mul_f32_e32 v135, 0xbfb8aa3b, v135
	v_mul_f32_e32 v0, 0xbfb8aa3b, v0
	v_exp_f32_e32 v135, v135
	v_exp_f32_e32 v0, v0
	v_add_f32_e32 v135, 1.0, v135
	v_add_f32_e32 v0, 1.0, v0
	v_rcp_f32_e32 v135, v135
	v_rcp_f32_e32 v0, v0
	v_mul_f32_e32 v135, v55, v135
	v_mul_f32_e32 v0, v54, v0
	v_cvt_pk_bf16_f32 v135, v0, v135
	global_store_dwordx4 v[162:163], v[132:135], off
	s_nop 0
	s_waitcnt vmcnt(14)
; __device__ __forceinline__ unsigned cvt_pk_bf16(float lo, float hi) { unsigned r; asm volatile("v_cvt_pk_bf16_f32 %0, %1, %2" : "=v"(r) : "v"(lo), "v"(hi)); return r; }
; __device__ __forceinline__ float sigm(float x) { return __builtin_amdgcn_rcpf(1.0f + __builtin_amdgcn_exp2f(-1.4426950408889634f * x)); }
;     __device__ __forceinline__ void operator()(f32x4 (&acc)[2][2][4][2], const Unit& u, int wr, int wc, int fr, int fq) const {
;     ...
;                     for (int bj = 0; bj < 2; ++bj) { const u32x4 gv = *(const u32x4*)(gb + off + bj * HALF);
;                         const f32x4 v0 = acc[ai][bj][m][0], v1 = acc[ai][bj][m][1];
;                         u32x4 w; w.x = cvt_pk_bf16(v0[0] * sigm(__uint_as_float(gv.x << 16)), v0[1] * sigm(__uint_as_float(gv.x & 0xffff0000u)));
;                         w.y = cvt_pk_bf16(v0[2] * sigm(__uint_as_float(gv.y << 16)), v0[3] * sigm(__uint_as_float(gv.y & 0xffff0000u)));
;                         w.z = cvt_pk_bf16(v1[0] * sigm(__uint_as_float(gv.z << 16)), v1[1] * sigm(__uint_as_float(gv.z & 0xffff0000u)));
;                         w.w = cvt_pk_bf16(v1[2] * sigm(__uint_as_float(gv.w << 16)), v1[3] * sigm(__uint_as_float(gv.w & 0xffff0000u)));
;                         *(u32x4*)(merged + off + bj * HALF) = w; } }
	v_mov_b32_e32 v132, v208
	v_mov_b32_e32 v133, v209
	v_mov_b32_e32 v134, v210
	v_mov_b32_e32 v135, v211
	v_lshlrev_b32_e32 v0, 16, v132
	v_and_b32_e32 v132, 0xffff0000, v132
	v_mul_f32_e32 v0, 0xbfb8aa3b, v0
	v_mul_f32_e32 v132, 0xbfb8aa3b, v132
	v_exp_f32_e32 v0, v0
	v_exp_f32_e32 v132, v132
	v_add_f32_e32 v0, 1.0, v0
	v_add_f32_e32 v132, 1.0, v132
	v_rcp_f32_e32 v0, v0
	v_rcp_f32_e32 v132, v132
	v_mul_f32_e32 v0, v24, v0
	v_mul_f32_e32 v132, v25, v132
	v_cvt_pk_bf16_f32 v132, v0, v132
	v_lshlrev_b32_e32 v0, 16, v133
	v_and_b32_e32 v133, 0xffff0000, v133
	v_mul_f32_e32 v0, 0xbfb8aa3b, v0
	v_mul_f32_e32 v133, 0xbfb8aa3b, v133
	v_exp_f32_e32 v0, v0
	v_exp_f32_e32 v133, v133
	v_add_f32_e32 v0, 1.0, v0
	v_add_f32_e32 v133, 1.0, v133
	v_rcp_f32_e32 v0, v0
	v_rcp_f32_e32 v133, v133
	v_mul_f32_e32 v0, v26, v0
	v_mul_f32_e32 v133, v27, v133
	v_cvt_pk_bf16_f32 v133, v0, v133
	v_lshlrev_b32_e32 v0, 16, v134
	v_and_b32_e32 v134, 0xffff0000, v134
	v_mul_f32_e32 v0, 0xbfb8aa3b, v0
	v_mul_f32_e32 v134, 0xbfb8aa3b, v134
	v_exp_f32_e32 v0, v0
	v_exp_f32_e32 v134, v134
	v_add_f32_e32 v0, 1.0, v0
	v_add_f32_e32 v134, 1.0, v134
	v_rcp_f32_e32 v0, v0
	v_rcp_f32_e32 v134, v134
	v_mul_f32_e32 v0, v20, v0
	v_mul_f32_e32 v134, v21, v134
	v_cvt_pk_bf16_f32 v134, v0, v134
	v_lshlrev_b32_e32 v0, 16, v135
	v_and_b32_e32 v135, 0xffff0000, v135
	v_mul_f32_e32 v135, 0xbfb8aa3b, v135
	v_mul_f32_e32 v0, 0xbfb8aa3b, v0
	v_exp_f32_e32 v135, v135
	v_exp_f32_e32 v0, v0
	v_add_f32_e32 v135, 1.0, v135
	v_add_f32_e32 v0, 1.0, v0
	v_rcp_f32_e32 v135, v135
	v_rcp_f32_e32 v0, v0
	v_mul_f32_e32 v135, v23, v135
	v_mul_f32_e32 v0, v22, v0
	v_cvt_pk_bf16_f32 v135, v0, v135
	global_store_dwordx4 v[162:163], v[132:135], off offset:256
	v_lshl_add_u64 v[162:163], v[158:159], 0, s[2:3]
	v_lshl_add_u64 v[160:161], s[74:75], 0, v[162:163]
	s_nop 0
	v_lshl_add_u64 v[162:163], s[92:93], 0, v[162:163]
	s_mov_b64 s[2:3], 0x58000
	s_waitcnt vmcnt(13)
	v_mov_b32_e32 v132, v212
	v_mov_b32_e32 v133, v213
	v_mov_b32_e32 v134, v214
	v_mov_b32_e32 v135, v215
	v_lshlrev_b32_e32 v0, 16, v132
	v_and_b32_e32 v132, 0xffff0000, v132
	v_mul_f32_e32 v0, 0xbfb8aa3b, v0
	v_mul_f32_e32 v132, 0xbfb8aa3b, v132
	v_exp_f32_e32 v0, v0
	v_exp_f32_e32 v132, v132
	v_add_f32_e32 v0, 1.0, v0
	v_add_f32_e32 v132, 1.0, v132
	v_rcp_f32_e32 v0, v0
	v_rcp_f32_e32 v132, v132
	v_mul_f32_e32 v0, v48, v0
	v_mul_f32_e32 v132, v49, v132
	v_cvt_pk_bf16_f32 v132, v0, v132
	v_lshlrev_b32_e32 v0, 16, v133
	v_and_b32_e32 v133, 0xffff0000, v133
	v_mul_f32_e32 v0, 0xbfb8aa3b, v0
	v_mul_f32_e32 v133, 0xbfb8aa3b, v133
	v_exp_f32_e32 v0, v0
	v_exp_f32_e32 v133, v133
	v_add_f32_e32 v0, 1.0, v0
	v_add_f32_e32 v133, 1.0, v133
	v_rcp_f32_e32 v0, v0
	v_rcp_f32_e32 v133, v133
	v_mul_f32_e32 v0, v50, v0
	v_mul_f32_e32 v133, v51, v133
	v_cvt_pk_bf16_f32 v133, v0, v133
	v_lshlrev_b32_e32 v0, 16, v134
	v_and_b32_e32 v134, 0xffff0000, v134
	v_mul_f32_e32 v0, 0xbfb8aa3b, v0
	v_mul_f32_e32 v134, 0xbfb8aa3b, v134
	v_exp_f32_e32 v0, v0
	v_exp_f32_e32 v134, v134
	v_add_f32_e32 v0, 1.0, v0
	v_add_f32_e32 v134, 1.0, v134
	v_rcp_f32_e32 v0, v0
	v_rcp_f32_e32 v134, v134
	v_mul_f32_e32 v0, v44, v0
	v_mul_f32_e32 v134, v45, v134
	v_cvt_pk_bf16_f32 v134, v0, v134
	v_lshlrev_b32_e32 v0, 16, v135
	v_and_b32_e32 v135, 0xffff0000, v135
	v_mul_f32_e32 v135, 0xbfb8aa3b, v135
	v_mul_f32_e32 v0, 0xbfb8aa3b, v0
	v_exp_f32_e32 v135, v135
	v_exp_f32_e32 v0, v0
	v_add_f32_e32 v135, 1.0, v135
	v_add_f32_e32 v0, 1.0, v0
	v_rcp_f32_e32 v135, v135
	v_rcp_f32_e32 v0, v0
	v_mul_f32_e32 v135, v47, v135
	v_mul_f32_e32 v0, v46, v0
	v_cvt_pk_bf16_f32 v135, v0, v135
	global_store_dwordx4 v[162:163], v[132:135], off
	s_nop 0
	s_waitcnt vmcnt(12)
	v_mov_b32_e32 v132, v216
	v_mov_b32_e32 v133, v217
	v_mov_b32_e32 v134, v218
	v_mov_b32_e32 v135, v219
	v_lshlrev_b32_e32 v0, 16, v132
	v_and_b32_e32 v132, 0xffff0000, v132
	v_mul_f32_e32 v0, 0xbfb8aa3b, v0
	v_mul_f32_e32 v132, 0xbfb8aa3b, v132
	v_exp_f32_e32 v0, v0
	v_exp_f32_e32 v132, v132
	v_add_f32_e32 v0, 1.0, v0
	v_add_f32_e32 v132, 1.0, v132
	v_rcp_f32_e32 v0, v0
	v_rcp_f32_e32 v132, v132
	v_mul_f32_e32 v0, v16, v0
	v_mul_f32_e32 v132, v17, v132
	v_cvt_pk_bf16_f32 v132, v0, v132
	v_lshlrev_b32_e32 v0, 16, v133
	v_and_b32_e32 v133, 0xffff0000, v133
	v_mul_f32_e32 v0, 0xbfb8aa3b, v0
	v_mul_f32_e32 v133, 0xbfb8aa3b, v133
	v_exp_f32_e32 v0, v0
	v_exp_f32_e32 v133, v133
	v_add_f32_e32 v0, 1.0, v0
	v_add_f32_e32 v133, 1.0, v133
	v_rcp_f32_e32 v0, v0
	v_rcp_f32_e32 v133, v133
	v_mul_f32_e32 v0, v18, v0
	v_mul_f32_e32 v133, v19, v133
	v_cvt_pk_bf16_f32 v133, v0, v133
	v_lshlrev_b32_e32 v0, 16, v134
	v_and_b32_e32 v134, 0xffff0000, v134
	v_mul_f32_e32 v0, 0xbfb8aa3b, v0
	v_mul_f32_e32 v134, 0xbfb8aa3b, v134
	v_exp_f32_e32 v0, v0
	v_exp_f32_e32 v134, v134
	v_add_f32_e32 v0, 1.0, v0
	v_add_f32_e32 v134, 1.0, v134
	v_rcp_f32_e32 v0, v0
	v_rcp_f32_e32 v134, v134
	v_mul_f32_e32 v0, v12, v0
	v_mul_f32_e32 v134, v13, v134
	v_cvt_pk_bf16_f32 v134, v0, v134
	v_lshlrev_b32_e32 v0, 16, v135
	v_and_b32_e32 v135, 0xffff0000, v135
	v_mul_f32_e32 v135, 0xbfb8aa3b, v135
	v_mul_f32_e32 v0, 0xbfb8aa3b, v0
	v_exp_f32_e32 v135, v135
	v_exp_f32_e32 v0, v0
	v_add_f32_e32 v135, 1.0, v135
	v_add_f32_e32 v0, 1.0, v0
	v_rcp_f32_e32 v135, v135
	v_rcp_f32_e32 v0, v0
	v_mul_f32_e32 v135, v15, v135
	v_mul_f32_e32 v0, v14, v0
	v_cvt_pk_bf16_f32 v135, v0, v135
	global_store_dwordx4 v[162:163], v[132:135], off offset:256
	v_lshl_add_u64 v[162:163], v[158:159], 0, s[2:3]
	v_lshl_add_u64 v[160:161], s[74:75], 0, v[162:163]
	s_nop 0
	v_lshl_add_u64 v[162:163], s[92:93], 0, v[162:163]
	s_waitcnt vmcnt(11)
; __device__ __forceinline__ unsigned cvt_pk_bf16(float lo, float hi) { unsigned r; asm volatile("v_cvt_pk_bf16_f32 %0, %1, %2" : "=v"(r) : "v"(lo), "v"(hi)); return r; }
; __device__ __forceinline__ float sigm(float x) { return __builtin_amdgcn_rcpf(1.0f + __builtin_amdgcn_exp2f(-1.4426950408889634f * x)); }
;     __device__ __forceinline__ void operator()(f32x4 (&acc)[2][2][4][2], const Unit& u, int wr, int wc, int fr, int fq) const {
;     ...
;                 for (int m = 0; m < 4; ++m) { const size_t off = (size_t)(row0 + ai * HALF + m * 16) * 1024 + col0;
; #pragma unroll
;                     for (int bj = 0; bj < 2; ++bj) { const u32x4 av = *(const u32x4*)(ga + off + bj * HALF), bv = *(const u32x4*)(gb + off + bj * HALF);
;                         const unsigned aw[4] = {av.x, av.y, av.z, av.w}, bw[4] = {bv.x, bv.y, bv.z, bv.w};
;     ...
;                     for (int bj = 0; bj < 2; ++bj) { const u32x4 gv = *(const u32x4*)(gb + off + bj * HALF);
;                         const f32x4 v0 = acc[ai][bj][m][0], v1 = acc[ai][bj][m][1];
;                         u32x4 w; w.x = cvt_pk_bf16(v0[0] * sigm(__uint_as_float(gv.x << 16)), v0[1] * sigm(__uint_as_float(gv.x & 0xffff0000u)));
;                         w.y = cvt_pk_bf16(v0[2] * sigm(__uint_as_float(gv.y << 16)), v0[3] * sigm(__uint_as_float(gv.y & 0xffff0000u)));
;                         w.z = cvt_pk_bf16(v1[0] * sigm(__uint_as_float(gv.z << 16)), v1[1] * sigm(__uint_as_float(gv.z & 0xffff0000u)));
;                         w.w = cvt_pk_bf16(v1[2] * sigm(__uint_as_float(gv.w << 16)), v1[3] * sigm(__uint_as_float(gv.w & 0xffff0000u)));
;                         *(u32x4*)(merged + off + bj * HALF) = w; } }
	v_mov_b32_e32 v132, v220
	v_mov_b32_e32 v133, v221
	v_mov_b32_e32 v134, v222
	v_mov_b32_e32 v135, v223
	v_lshlrev_b32_e32 v0, 16, v132
	v_and_b32_e32 v132, 0xffff0000, v132
	v_mul_f32_e32 v0, 0xbfb8aa3b, v0
	v_mul_f32_e32 v132, 0xbfb8aa3b, v132
	v_exp_f32_e32 v0, v0
	v_exp_f32_e32 v132, v132
	v_add_f32_e32 v0, 1.0, v0
	v_add_f32_e32 v132, 1.0, v132
	v_rcp_f32_e32 v0, v0
	v_rcp_f32_e32 v132, v132
	v_mul_f32_e32 v0, v40, v0
	v_mul_f32_e32 v132, v41, v132
	v_cvt_pk_bf16_f32 v132, v0, v132
	v_lshlrev_b32_e32 v0, 16, v133
	v_and_b32_e32 v133, 0xffff0000, v133
	v_mul_f32_e32 v0, 0xbfb8aa3b, v0
	v_mul_f32_e32 v133, 0xbfb8aa3b, v133
	v_exp_f32_e32 v0, v0
	v_exp_f32_e32 v133, v133
	v_add_f32_e32 v0, 1.0, v0
	v_add_f32_e32 v133, 1.0, v133
	v_rcp_f32_e32 v0, v0
	v_rcp_f32_e32 v133, v133
	v_mul_f32_e32 v0, v42, v0
	v_mul_f32_e32 v133, v43, v133
	v_cvt_pk_bf16_f32 v133, v0, v133
	v_lshlrev_b32_e32 v0, 16, v134
	v_and_b32_e32 v134, 0xffff0000, v134
	v_mul_f32_e32 v0, 0xbfb8aa3b, v0
	v_mul_f32_e32 v134, 0xbfb8aa3b, v134
	v_exp_f32_e32 v0, v0
	v_exp_f32_e32 v134, v134
	v_add_f32_e32 v0, 1.0, v0
	v_add_f32_e32 v134, 1.0, v134
	v_rcp_f32_e32 v0, v0
	v_rcp_f32_e32 v134, v134
	v_mul_f32_e32 v0, v36, v0
	v_mul_f32_e32 v134, v37, v134
	v_cvt_pk_bf16_f32 v134, v0, v134
	v_lshlrev_b32_e32 v0, 16, v135
	v_and_b32_e32 v135, 0xffff0000, v135
	v_mul_f32_e32 v135, 0xbfb8aa3b, v135
	v_mul_f32_e32 v0, 0xbfb8aa3b, v0
	v_exp_f32_e32 v135, v135
	v_exp_f32_e32 v0, v0
	v_add_f32_e32 v135, 1.0, v135
	v_add_f32_e32 v0, 1.0, v0
	v_rcp_f32_e32 v135, v135
	v_rcp_f32_e32 v0, v0
	v_mul_f32_e32 v135, v39, v135
	v_mul_f32_e32 v0, v38, v0
	v_cvt_pk_bf16_f32 v135, v0, v135
	global_store_dwordx4 v[162:163], v[132:135], off
	s_nop 0
	s_waitcnt vmcnt(10)
	v_mov_b32_e32 v132, v224
	v_mov_b32_e32 v133, v225
	v_mov_b32_e32 v134, v226
	v_mov_b32_e32 v135, v227
	v_lshlrev_b32_e32 v0, 16, v132
	v_and_b32_e32 v132, 0xffff0000, v132
	v_mul_f32_e32 v0, 0xbfb8aa3b, v0
	v_mul_f32_e32 v132, 0xbfb8aa3b, v132
	v_exp_f32_e32 v0, v0
	v_exp_f32_e32 v132, v132
	v_add_f32_e32 v0, 1.0, v0
	v_add_f32_e32 v132, 1.0, v132
	v_rcp_f32_e32 v0, v0
	v_rcp_f32_e32 v132, v132
	v_mul_f32_e32 v0, v8, v0
	v_mul_f32_e32 v132, v9, v132
	v_cvt_pk_bf16_f32 v132, v0, v132
	v_lshlrev_b32_e32 v0, 16, v133
	v_and_b32_e32 v133, 0xffff0000, v133
	v_mul_f32_e32 v0, 0xbfb8aa3b, v0
	v_mul_f32_e32 v133, 0xbfb8aa3b, v133
	v_exp_f32_e32 v0, v0
	v_exp_f32_e32 v133, v133
	v_add_f32_e32 v0, 1.0, v0
	v_add_f32_e32 v133, 1.0, v133
	v_rcp_f32_e32 v0, v0
	v_rcp_f32_e32 v133, v133
	v_mul_f32_e32 v0, v10, v0
	v_mul_f32_e32 v133, v11, v133
	v_cvt_pk_bf16_f32 v133, v0, v133
	v_lshlrev_b32_e32 v0, 16, v134
	v_and_b32_e32 v134, 0xffff0000, v134
	v_mul_f32_e32 v0, 0xbfb8aa3b, v0
	v_mul_f32_e32 v134, 0xbfb8aa3b, v134
	v_exp_f32_e32 v0, v0
	v_exp_f32_e32 v134, v134
	v_add_f32_e32 v0, 1.0, v0
	v_add_f32_e32 v134, 1.0, v134
	v_rcp_f32_e32 v0, v0
	v_rcp_f32_e32 v134, v134
	v_mul_f32_e32 v0, v4, v0
	v_mul_f32_e32 v134, v5, v134
	v_cvt_pk_bf16_f32 v134, v0, v134
	v_lshlrev_b32_e32 v0, 16, v135
	v_and_b32_e32 v135, 0xffff0000, v135
	v_mul_f32_e32 v135, 0xbfb8aa3b, v135
	v_mul_f32_e32 v0, 0xbfb8aa3b, v0
	v_exp_f32_e32 v135, v135
	v_exp_f32_e32 v0, v0
	v_add_f32_e32 v135, 1.0, v135
	v_add_f32_e32 v0, 1.0, v0
	v_rcp_f32_e32 v135, v135
	v_rcp_f32_e32 v0, v0
	v_mul_f32_e32 v135, v7, v135
	v_mul_f32_e32 v0, v6, v0
	v_cvt_pk_bf16_f32 v135, v0, v135
	global_store_dwordx4 v[162:163], v[132:135], off offset:256
	s_cbranch_execnz .LBB0_582
.LBB0_581:
	v_readlane_b32 s2, v249, 40
	v_readlane_b32 s3, v249, 41
	s_mov_b64 s[18:19], 0x48000
	s_nop 0
	v_lshl_add_u64 v[162:163], s[2:3], 0, v[158:159]
	v_mov_b32_e32 v184, 0x8000
	v_mov_b32_e32 v185, 0
	v_mov_b32_e32 v186, 0x28000
	v_mov_b32_e32 v187, 0
	v_mov_b32_e32 v180, v162
	v_mov_b32_e32 v181, v163
	v_mov_b32_e32 v182, v156
	v_mov_b32_e32 v183, v157
	global_load_dwordx4 v[204:207], v[180:181], off
	global_load_dwordx4 v[208:211], v[182:183], off
	global_load_dwordx4 v[212:215], v[180:181], off offset:256
	global_load_dwordx4 v[216:219], v[182:183], off offset:256
	v_lshl_add_u64 v[180:181], v[180:181], 0, v[184:185]
	v_lshl_add_u64 v[182:183], v[182:183], 0, v[184:185]
	global_load_dwordx4 v[220:223], v[180:181], off
	global_load_dwordx4 v[224:227], v[182:183], off
	global_load_dwordx4 v[228:231], v[180:181], off offset:256
	global_load_dwordx4 v[232:235], v[182:183], off offset:256
	v_lshl_add_u64 v[180:181], v[180:181], 0, v[184:185]
	v_lshl_add_u64 v[182:183], v[182:183], 0, v[184:185]
	global_load_dwordx4 v[236:239], v[180:181], off
	global_load_dwordx4 v[240:243], v[182:183], off
	s_nop 0
	s_nop 0
	s_waitcnt vmcnt(8)
; __device__ __forceinline__ float en2(unsigned hbits) { return __builtin_amdgcn_exp2f(-1.4426950408889634f * __uint_as_float(hbits)); }
;     __device__ __forceinline__ void operator()(f32x4 (&acc)[2][2][4][2], const Unit& u, int wr, int wc, int fr, int fq) const {
;     ...
;                 for (int m = 0; m < 4; ++m) { const size_t off = (size_t)(row0 + ai * HALF + m * 16) * 1024 + col0;
; #pragma unroll
;                     for (int bj = 0; bj < 2; ++bj) { const u32x4 av = *(const u32x4*)(ga + off + bj * HALF), bv = *(const u32x4*)(gb + off + bj * HALF);
;                         const unsigned aw[4] = {av.x, av.y, av.z, av.w}, bw[4] = {bv.x, bv.y, bv.z, bv.w};
; #pragma unroll
;                         for (int q = 0; q < 4; ++q) { const int n = q >> 1, e = (q & 1) * 2;
;                             const float r0 = (1.0f + en2(bw[q] << 16)) * __builtin_amdgcn_rcpf(1.0f + en2(aw[q] << 16));
;                             const float r1 = (1.0f + en2(bw[q] & 0xffff0000u)) * __builtin_amdgcn_rcpf(1.0f + en2(aw[q] & 0xffff0000u));
;                             acc[ai][bj][m][n][e] *= r0; acc[ai][bj][m][n][e + 1] *= r1; } } }
	v_mov_b32_e32 v132, v204
	v_mov_b32_e32 v133, v205
	v_mov_b32_e32 v134, v206
	v_mov_b32_e32 v135, v207
	v_mov_b32_e32 v158, v208
	v_mov_b32_e32 v159, v209
	v_mov_b32_e32 v160, v210
	v_mov_b32_e32 v161, v211
	global_load_dwordx4 v[204:207], v[180:181], off offset:256
	global_load_dwordx4 v[208:211], v[182:183], off offset:256
	v_lshl_add_u64 v[180:181], v[180:181], 0, v[184:185]
	v_lshl_add_u64 v[182:183], v[182:183], 0, v[184:185]
	v_lshlrev_b32_e32 v0, 16, v158
	v_mul_f32_e32 v0, 0xbfb8aa3b, v0
	v_exp_f32_e32 v168, v0
	v_lshlrev_b32_e32 v0, 16, v132
	v_mul_f32_e32 v0, 0xbfb8aa3b, v0
	v_exp_f32_e32 v0, v0
	s_nop 0
	v_add_f32_e32 v0, 1.0, v0
	v_rcp_f32_e32 v170, v0
	v_and_b32_e32 v0, 0xffff0000, v158
	v_mul_f32_e32 v0, 0xbfb8aa3b, v0
	v_exp_f32_e32 v169, v0
	v_and_b32_e32 v0, 0xffff0000, v132
	v_mul_f32_e32 v0, 0xbfb8aa3b, v0
	v_exp_f32_e32 v0, v0
	v_pk_add_f32 v[168:169], v[168:169], 1.0 op_sel_hi:[1,0]
	v_add_f32_e32 v0, 1.0, v0
	v_rcp_f32_e32 v171, v0
	v_lshlrev_b32_e32 v0, 16, v159
	v_mul_f32_e32 v0, 0xbfb8aa3b, v0
	v_exp_f32_e32 v158, v0
	v_lshlrev_b32_e32 v0, 16, v133
	v_mul_f32_e32 v0, 0xbfb8aa3b, v0
	v_exp_f32_e32 v0, v0
	v_pk_mul_f32 v[168:169], v[170:171], v[168:169]
	v_add_f32_e32 v0, 1.0, v0
	v_rcp_f32_e32 v132, v0
	v_and_b32_e32 v0, 0xffff0000, v159
	v_mul_f32_e32 v0, 0xbfb8aa3b, v0
	v_exp_f32_e32 v159, v0
	v_and_b32_e32 v0, 0xffff0000, v133
	v_mul_f32_e32 v0, 0xbfb8aa3b, v0
	v_exp_f32_e32 v0, v0
	v_pk_add_f32 v[158:159], v[158:159], 1.0 op_sel_hi:[1,0]
	v_pk_mul_f32 v[128:129], v[128:129], v[168:169]
	v_add_f32_e32 v0, 1.0, v0
	v_rcp_f32_e32 v133, v0
	v_lshlrev_b32_e32 v0, 16, v160
	v_mul_f32_e32 v0, 0xbfb8aa3b, v0
	v_pk_mul_f32 v[132:133], v[132:133], v[158:159]
	s_nop 0
	v_pk_mul_f32 v[130:131], v[130:131], v[132:133]
	v_exp_f32_e32 v132, v0
	v_lshlrev_b32_e32 v0, 16, v134
	v_mul_f32_e32 v0, 0xbfb8aa3b, v0
	v_exp_f32_e32 v0, v0
	s_nop 0
	v_add_f32_e32 v0, 1.0, v0
	v_rcp_f32_e32 v158, v0
	v_and_b32_e32 v0, 0xffff0000, v160
	v_mul_f32_e32 v0, 0xbfb8aa3b, v0
	v_exp_f32_e32 v133, v0
	v_and_b32_e32 v0, 0xffff0000, v134
	v_mul_f32_e32 v0, 0xbfb8aa3b, v0
	v_exp_f32_e32 v0, v0
	v_pk_add_f32 v[132:133], v[132:133], 1.0 op_sel_hi:[1,0]
	v_add_f32_e32 v0, 1.0, v0
	v_rcp_f32_e32 v159, v0
	v_lshlrev_b32_e32 v0, 16, v161
	v_mul_f32_e32 v0, 0xbfb8aa3b, v0
	v_exp_f32_e32 v160, v0
	v_lshlrev_b32_e32 v0, 16, v135
	v_mul_f32_e32 v0, 0xbfb8aa3b, v0
	v_exp_f32_e32 v0, v0
	v_pk_mul_f32 v[132:133], v[158:159], v[132:133]
	v_add_f32_e32 v0, 1.0, v0
	v_rcp_f32_e32 v134, v0
	v_and_b32_e32 v0, 0xffff0000, v161
	v_mul_f32_e32 v0, 0xbfb8aa3b, v0
	v_exp_f32_e32 v161, v0
	v_and_b32_e32 v0, 0xffff0000, v135
	v_mul_f32_e32 v0, 0xbfb8aa3b, v0
	v_exp_f32_e32 v0, v0
	v_pk_add_f32 v[160:161], v[160:161], 1.0 op_sel_hi:[1,0]
	v_pk_mul_f32 v[124:125], v[124:125], v[132:133]
	v_add_f32_e32 v0, 1.0, v0
	v_rcp_f32_e32 v135, v0
	s_nop 0
	v_pk_mul_f32 v[134:135], v[134:135], v[160:161]
	s_nop 0
	v_pk_mul_f32 v[126:127], v[126:127], v[134:135]
	s_nop 0
	s_nop 0
	s_nop 0
	s_waitcnt vmcnt(8)
	v_mov_b32_e32 v132, v212
	v_mov_b32_e32 v133, v213
	v_mov_b32_e32 v134, v214
	v_mov_b32_e32 v135, v215
	v_mov_b32_e32 v156, v216
	v_mov_b32_e32 v157, v217
	v_mov_b32_e32 v158, v218
	v_mov_b32_e32 v159, v219
	global_load_dwordx4 v[212:215], v[180:181], off
	global_load_dwordx4 v[216:219], v[182:183], off
	v_lshlrev_b32_e32 v0, 16, v156
	v_mul_f32_e32 v0, 0xbfb8aa3b, v0
	v_exp_f32_e32 v160, v0
	v_lshlrev_b32_e32 v0, 16, v132
	v_mul_f32_e32 v0, 0xbfb8aa3b, v0
	v_exp_f32_e32 v0, v0
	s_nop 0
	v_add_f32_e32 v0, 1.0, v0
	v_rcp_f32_e32 v162, v0
	v_and_b32_e32 v0, 0xffff0000, v156
	v_mul_f32_e32 v0, 0xbfb8aa3b, v0
	v_exp_f32_e32 v161, v0
	v_and_b32_e32 v0, 0xffff0000, v132
	v_mul_f32_e32 v0, 0xbfb8aa3b, v0
	v_exp_f32_e32 v0, v0
	v_pk_add_f32 v[160:161], v[160:161], 1.0 op_sel_hi:[1,0]
	v_add_f32_e32 v0, 1.0, v0
	v_rcp_f32_e32 v163, v0
	v_lshlrev_b32_e32 v0, 16, v157
	v_mul_f32_e32 v0, 0xbfb8aa3b, v0
	v_exp_f32_e32 v156, v0
	v_lshlrev_b32_e32 v0, 16, v133
	v_mul_f32_e32 v0, 0xbfb8aa3b, v0
	v_exp_f32_e32 v0, v0
	v_pk_mul_f32 v[160:161], v[160:161], v[162:163]
	v_add_f32_e32 v0, 1.0, v0
	v_rcp_f32_e32 v132, v0
	v_and_b32_e32 v0, 0xffff0000, v157
	v_mul_f32_e32 v0, 0xbfb8aa3b, v0
	v_exp_f32_e32 v157, v0
	v_and_b32_e32 v0, 0xffff0000, v133
	v_mul_f32_e32 v0, 0xbfb8aa3b, v0
	v_exp_f32_e32 v0, v0
	v_pk_add_f32 v[156:157], v[156:157], 1.0 op_sel_hi:[1,0]
	v_pk_mul_f32 v[96:97], v[96:97], v[160:161]
	v_add_f32_e32 v0, 1.0, v0
	v_rcp_f32_e32 v133, v0
	v_lshlrev_b32_e32 v0, 16, v158
	v_mul_f32_e32 v0, 0xbfb8aa3b, v0
	v_pk_mul_f32 v[132:133], v[156:157], v[132:133]
	s_nop 0
	v_pk_mul_f32 v[98:99], v[98:99], v[132:133]
	v_exp_f32_e32 v132, v0
	v_lshlrev_b32_e32 v0, 16, v134
	v_mul_f32_e32 v0, 0xbfb8aa3b, v0
	v_exp_f32_e32 v0, v0
	s_nop 0
	v_add_f32_e32 v0, 1.0, v0
	v_rcp_f32_e32 v156, v0
	v_and_b32_e32 v0, 0xffff0000, v158
	v_mul_f32_e32 v0, 0xbfb8aa3b, v0
	v_exp_f32_e32 v133, v0
	v_and_b32_e32 v0, 0xffff0000, v134
	v_mul_f32_e32 v0, 0xbfb8aa3b, v0
	v_exp_f32_e32 v0, v0
	v_pk_add_f32 v[132:133], v[132:133], 1.0 op_sel_hi:[1,0]
	v_add_f32_e32 v0, 1.0, v0
	v_rcp_f32_e32 v157, v0
	v_lshlrev_b32_e32 v0, 16, v159
	v_mul_f32_e32 v0, 0xbfb8aa3b, v0
	v_exp_f32_e32 v158, v0
	v_lshlrev_b32_e32 v0, 16, v135
	v_mul_f32_e32 v0, 0xbfb8aa3b, v0
	v_exp_f32_e32 v0, v0
	v_pk_mul_f32 v[132:133], v[132:133], v[156:157]
	v_add_f32_e32 v0, 1.0, v0
	v_rcp_f32_e32 v134, v0
	v_and_b32_e32 v0, 0xffff0000, v159
	v_mul_f32_e32 v0, 0xbfb8aa3b, v0
	v_exp_f32_e32 v159, v0
	v_and_b32_e32 v0, 0xffff0000, v135
	v_mul_f32_e32 v0, 0xbfb8aa3b, v0
	v_exp_f32_e32 v0, v0
	v_pk_mul_f32 v[92:93], v[92:93], v[132:133]
	v_lshlrev_b64 v[132:133], 10, v[154:155]
	v_pk_add_f32 v[158:159], v[158:159], 1.0 op_sel_hi:[1,0]
	v_add_f32_e32 v0, 1.0, v0
	v_rcp_f32_e32 v135, v0
	v_lshl_add_u64 v[132:133], v[132:133], 0, v[2:3]
	v_lshlrev_b64 v[132:133], 1, v[132:133]
	v_pk_mul_f32 v[134:135], v[158:159], v[134:135]
	s_nop 0
	v_pk_mul_f32 v[94:95], v[94:95], v[134:135]
	v_lshl_add_u64 v[134:135], s[2:3], 0, v[132:133]
	v_lshl_add_u64 v[132:133], s[74:75], 0, v[132:133]
	s_nop 0
	s_nop 0
	s_waitcnt vmcnt(8)
; __device__ __forceinline__ float en2(unsigned hbits) { return __builtin_amdgcn_exp2f(-1.4426950408889634f * __uint_as_float(hbits)); }
;     __device__ __forceinline__ void operator()(f32x4 (&acc)[2][2][4][2], const Unit& u, int wr, int wc, int fr, int fq) const {
;     ...
;                 for (int m = 0; m < 4; ++m) { const size_t off = (size_t)(row0 + ai * HALF + m * 16) * 1024 + col0;
; #pragma unroll
;                     for (int bj = 0; bj < 2; ++bj) { const u32x4 av = *(const u32x4*)(ga + off + bj * HALF), bv = *(const u32x4*)(gb + off + bj * HALF);
;                         const unsigned aw[4] = {av.x, av.y, av.z, av.w}, bw[4] = {bv.x, bv.y, bv.z, bv.w};
; #pragma unroll
;                         for (int q = 0; q < 4; ++q) { const int n = q >> 1, e = (q & 1) * 2;
;                             const float r0 = (1.0f + en2(bw[q] << 16)) * __builtin_amdgcn_rcpf(1.0f + en2(aw[q] << 16));
;                             const float r1 = (1.0f + en2(bw[q] & 0xffff0000u)) * __builtin_amdgcn_rcpf(1.0f + en2(aw[q] & 0xffff0000u));
;                             acc[ai][bj][m][n][e] *= r0; acc[ai][bj][m][n][e + 1] *= r1; } } }
	v_mov_b32_e32 v154, v220
	v_mov_b32_e32 v155, v221
	v_mov_b32_e32 v156, v222
	v_mov_b32_e32 v157, v223
	v_mov_b32_e32 v158, v224
	v_mov_b32_e32 v159, v225
	v_mov_b32_e32 v160, v226
	v_mov_b32_e32 v161, v227
	global_load_dwordx4 v[220:223], v[180:181], off offset:256
	global_load_dwordx4 v[224:227], v[182:183], off offset:256
	v_lshl_add_u64 v[180:181], v[180:181], 0, v[186:187]
	v_lshl_add_u64 v[182:183], v[182:183], 0, v[186:187]
	v_lshlrev_b32_e32 v0, 16, v158
	v_mul_f32_e32 v0, 0xbfb8aa3b, v0
	v_exp_f32_e32 v162, v0
	v_lshlrev_b32_e32 v0, 16, v154
	v_mul_f32_e32 v0, 0xbfb8aa3b, v0
	v_exp_f32_e32 v0, v0
	s_nop 0
	v_add_f32_e32 v0, 1.0, v0
	v_rcp_f32_e32 v168, v0
	v_and_b32_e32 v0, 0xffff0000, v158
	v_mul_f32_e32 v0, 0xbfb8aa3b, v0
	v_exp_f32_e32 v163, v0
	v_and_b32_e32 v0, 0xffff0000, v154
	v_mul_f32_e32 v0, 0xbfb8aa3b, v0
	v_exp_f32_e32 v0, v0
	v_pk_add_f32 v[162:163], v[162:163], 1.0 op_sel_hi:[1,0]
	v_add_f32_e32 v0, 1.0, v0
	v_rcp_f32_e32 v169, v0
	v_lshlrev_b32_e32 v0, 16, v159
	v_mul_f32_e32 v0, 0xbfb8aa3b, v0
	v_exp_f32_e32 v158, v0
	v_lshlrev_b32_e32 v0, 16, v155
	v_mul_f32_e32 v0, 0xbfb8aa3b, v0
	v_exp_f32_e32 v0, v0
	v_pk_mul_f32 v[162:163], v[162:163], v[168:169]
	v_add_f32_e32 v0, 1.0, v0
	v_rcp_f32_e32 v154, v0
	v_and_b32_e32 v0, 0xffff0000, v159
	v_mul_f32_e32 v0, 0xbfb8aa3b, v0
	v_exp_f32_e32 v159, v0
	v_and_b32_e32 v0, 0xffff0000, v155
	v_mul_f32_e32 v0, 0xbfb8aa3b, v0
	v_exp_f32_e32 v0, v0
	v_pk_add_f32 v[158:159], v[158:159], 1.0 op_sel_hi:[1,0]
	v_pk_mul_f32 v[120:121], v[120:121], v[162:163]
	v_add_f32_e32 v0, 1.0, v0
	v_rcp_f32_e32 v155, v0
	v_lshlrev_b32_e32 v0, 16, v160
	v_mul_f32_e32 v0, 0xbfb8aa3b, v0
	v_pk_mul_f32 v[154:155], v[158:159], v[154:155]
	s_nop 0
	v_pk_mul_f32 v[122:123], v[122:123], v[154:155]
	v_exp_f32_e32 v154, v0
	v_lshlrev_b32_e32 v0, 16, v156
	v_mul_f32_e32 v0, 0xbfb8aa3b, v0
	v_exp_f32_e32 v0, v0
	s_nop 0
	v_add_f32_e32 v0, 1.0, v0
	v_rcp_f32_e32 v158, v0
	v_and_b32_e32 v0, 0xffff0000, v160
	v_mul_f32_e32 v0, 0xbfb8aa3b, v0
	v_exp_f32_e32 v155, v0
	v_and_b32_e32 v0, 0xffff0000, v156
	v_mul_f32_e32 v0, 0xbfb8aa3b, v0
	v_exp_f32_e32 v0, v0
	v_pk_add_f32 v[154:155], v[154:155], 1.0 op_sel_hi:[1,0]
	v_add_f32_e32 v0, 1.0, v0
	v_rcp_f32_e32 v159, v0
	v_lshlrev_b32_e32 v0, 16, v161
	v_mul_f32_e32 v0, 0xbfb8aa3b, v0
	v_exp_f32_e32 v160, v0
	v_lshlrev_b32_e32 v0, 16, v157
	v_mul_f32_e32 v0, 0xbfb8aa3b, v0
	v_exp_f32_e32 v0, v0
	v_pk_mul_f32 v[154:155], v[154:155], v[158:159]
	v_add_f32_e32 v0, 1.0, v0
	v_rcp_f32_e32 v156, v0
	v_and_b32_e32 v0, 0xffff0000, v161
	v_mul_f32_e32 v0, 0xbfb8aa3b, v0
	v_exp_f32_e32 v161, v0
	v_and_b32_e32 v0, 0xffff0000, v157
	v_mul_f32_e32 v0, 0xbfb8aa3b, v0
	v_exp_f32_e32 v0, v0
	v_pk_add_f32 v[160:161], v[160:161], 1.0 op_sel_hi:[1,0]
	v_pk_mul_f32 v[116:117], v[116:117], v[154:155]
	v_add_f32_e32 v0, 1.0, v0
	v_rcp_f32_e32 v157, v0
	s_nop 0
	v_pk_mul_f32 v[156:157], v[160:161], v[156:157]
	s_nop 0
	v_pk_mul_f32 v[118:119], v[118:119], v[156:157]
	s_nop 0
	s_nop 0
	s_nop 0
	s_waitcnt vmcnt(8)
	v_mov_b32_e32 v154, v228
	v_mov_b32_e32 v155, v229
	v_mov_b32_e32 v156, v230
	v_mov_b32_e32 v157, v231
	v_mov_b32_e32 v132, v232
	v_mov_b32_e32 v133, v233
	v_mov_b32_e32 v134, v234
	v_mov_b32_e32 v135, v235
	global_load_dwordx4 v[228:231], v[180:181], off
	global_load_dwordx4 v[232:235], v[182:183], off
	v_lshlrev_b32_e32 v0, 16, v132
	v_mul_f32_e32 v0, 0xbfb8aa3b, v0
	v_exp_f32_e32 v158, v0
	v_lshlrev_b32_e32 v0, 16, v154
	v_mul_f32_e32 v0, 0xbfb8aa3b, v0
	v_exp_f32_e32 v0, v0
	s_nop 0
	v_add_f32_e32 v0, 1.0, v0
	v_rcp_f32_e32 v160, v0
	v_and_b32_e32 v0, 0xffff0000, v132
	v_mul_f32_e32 v0, 0xbfb8aa3b, v0
	v_exp_f32_e32 v159, v0
	v_and_b32_e32 v0, 0xffff0000, v154
	v_mul_f32_e32 v0, 0xbfb8aa3b, v0
	v_exp_f32_e32 v0, v0
	v_pk_add_f32 v[158:159], v[158:159], 1.0 op_sel_hi:[1,0]
	v_add_f32_e32 v0, 1.0, v0
	v_rcp_f32_e32 v161, v0
	v_lshlrev_b32_e32 v0, 16, v133
	v_mul_f32_e32 v0, 0xbfb8aa3b, v0
	v_exp_f32_e32 v132, v0
	v_lshlrev_b32_e32 v0, 16, v155
	v_mul_f32_e32 v0, 0xbfb8aa3b, v0
	v_exp_f32_e32 v0, v0
	v_pk_mul_f32 v[158:159], v[158:159], v[160:161]
	v_add_f32_e32 v0, 1.0, v0
	v_rcp_f32_e32 v154, v0
	v_and_b32_e32 v0, 0xffff0000, v133
	v_mul_f32_e32 v0, 0xbfb8aa3b, v0
	v_exp_f32_e32 v133, v0
	v_and_b32_e32 v0, 0xffff0000, v155
	v_mul_f32_e32 v0, 0xbfb8aa3b, v0
	v_exp_f32_e32 v0, v0
	v_pk_add_f32 v[132:133], v[132:133], 1.0 op_sel_hi:[1,0]
	v_pk_mul_f32 v[88:89], v[88:89], v[158:159]
	v_add_f32_e32 v0, 1.0, v0
	v_rcp_f32_e32 v155, v0
	v_lshlrev_b32_e32 v0, 16, v134
	v_mul_f32_e32 v0, 0xbfb8aa3b, v0
	v_pk_mul_f32 v[132:133], v[132:133], v[154:155]
	s_nop 0
	v_pk_mul_f32 v[90:91], v[90:91], v[132:133]
	v_exp_f32_e32 v132, v0
	v_lshlrev_b32_e32 v0, 16, v156
	v_mul_f32_e32 v0, 0xbfb8aa3b, v0
	v_exp_f32_e32 v0, v0
	s_nop 0
	v_add_f32_e32 v0, 1.0, v0
	v_rcp_f32_e32 v154, v0
	v_and_b32_e32 v0, 0xffff0000, v134
	v_mul_f32_e32 v0, 0xbfb8aa3b, v0
	v_exp_f32_e32 v133, v0
	v_and_b32_e32 v0, 0xffff0000, v156
	v_mul_f32_e32 v0, 0xbfb8aa3b, v0
	v_exp_f32_e32 v0, v0
	v_pk_add_f32 v[132:133], v[132:133], 1.0 op_sel_hi:[1,0]
	v_add_f32_e32 v0, 1.0, v0
	v_rcp_f32_e32 v155, v0
	v_lshlrev_b32_e32 v0, 16, v135
	v_mul_f32_e32 v0, 0xbfb8aa3b, v0
	v_exp_f32_e32 v134, v0
	v_lshlrev_b32_e32 v0, 16, v157
	v_mul_f32_e32 v0, 0xbfb8aa3b, v0
	v_exp_f32_e32 v0, v0
	v_pk_mul_f32 v[132:133], v[132:133], v[154:155]
	v_add_f32_e32 v0, 1.0, v0
	v_rcp_f32_e32 v156, v0
	v_and_b32_e32 v0, 0xffff0000, v135
	v_mul_f32_e32 v0, 0xbfb8aa3b, v0
	v_exp_f32_e32 v135, v0
	v_and_b32_e32 v0, 0xffff0000, v157
	v_mul_f32_e32 v0, 0xbfb8aa3b, v0
	v_exp_f32_e32 v0, v0
	v_pk_mul_f32 v[84:85], v[84:85], v[132:133]
	v_lshlrev_b64 v[132:133], 10, v[152:153]
	v_pk_add_f32 v[134:135], v[134:135], 1.0 op_sel_hi:[1,0]
	v_add_f32_e32 v0, 1.0, v0
	v_rcp_f32_e32 v157, v0
	v_lshl_add_u64 v[132:133], v[132:133], 0, v[2:3]
	v_lshlrev_b64 v[132:133], 1, v[132:133]
	v_pk_mul_f32 v[134:135], v[134:135], v[156:157]
	s_nop 0
	v_pk_mul_f32 v[86:87], v[86:87], v[134:135]
	v_lshl_add_u64 v[134:135], s[2:3], 0, v[132:133]
	v_lshl_add_u64 v[132:133], s[74:75], 0, v[132:133]
	s_nop 0
	s_nop 0
	s_waitcnt vmcnt(8)
; __device__ __forceinline__ float en2(unsigned hbits) { return __builtin_amdgcn_exp2f(-1.4426950408889634f * __uint_as_float(hbits)); }
;     __device__ __forceinline__ void operator()(f32x4 (&acc)[2][2][4][2], const Unit& u, int wr, int wc, int fr, int fq) const {
;     ...
;                 for (int m = 0; m < 4; ++m) { const size_t off = (size_t)(row0 + ai * HALF + m * 16) * 1024 + col0;
; #pragma unroll
;                     for (int bj = 0; bj < 2; ++bj) { const u32x4 av = *(const u32x4*)(ga + off + bj * HALF), bv = *(const u32x4*)(gb + off + bj * HALF);
;                         const unsigned aw[4] = {av.x, av.y, av.z, av.w}, bw[4] = {bv.x, bv.y, bv.z, bv.w};
; #pragma unroll
;                         for (int q = 0; q < 4; ++q) { const int n = q >> 1, e = (q & 1) * 2;
;                             const float r0 = (1.0f + en2(bw[q] << 16)) * __builtin_amdgcn_rcpf(1.0f + en2(aw[q] << 16));
;                             const float r1 = (1.0f + en2(bw[q] & 0xffff0000u)) * __builtin_amdgcn_rcpf(1.0f + en2(aw[q] & 0xffff0000u));
;                             acc[ai][bj][m][n][e] *= r0; acc[ai][bj][m][n][e + 1] *= r1; } } }
	v_mov_b32_e32 v152, v236
	v_mov_b32_e32 v153, v237
	v_mov_b32_e32 v154, v238
	v_mov_b32_e32 v155, v239
	v_mov_b32_e32 v156, v240
	v_mov_b32_e32 v157, v241
	v_mov_b32_e32 v158, v242
	v_mov_b32_e32 v159, v243
	global_load_dwordx4 v[236:239], v[180:181], off offset:256
	global_load_dwordx4 v[240:243], v[182:183], off offset:256
	v_lshl_add_u64 v[180:181], v[180:181], 0, v[184:185]
	v_lshl_add_u64 v[182:183], v[182:183], 0, v[184:185]
	v_lshlrev_b32_e32 v0, 16, v156
	v_mul_f32_e32 v0, 0xbfb8aa3b, v0
	v_exp_f32_e32 v160, v0
	v_lshlrev_b32_e32 v0, 16, v152
	v_mul_f32_e32 v0, 0xbfb8aa3b, v0
	v_exp_f32_e32 v0, v0
	s_nop 0
	v_add_f32_e32 v0, 1.0, v0
	v_rcp_f32_e32 v162, v0
	v_and_b32_e32 v0, 0xffff0000, v156
	v_mul_f32_e32 v0, 0xbfb8aa3b, v0
	v_exp_f32_e32 v161, v0
	v_and_b32_e32 v0, 0xffff0000, v152
	v_mul_f32_e32 v0, 0xbfb8aa3b, v0
	v_exp_f32_e32 v0, v0
	v_pk_add_f32 v[160:161], v[160:161], 1.0 op_sel_hi:[1,0]
	v_add_f32_e32 v0, 1.0, v0
	v_rcp_f32_e32 v163, v0
	v_lshlrev_b32_e32 v0, 16, v157
	v_mul_f32_e32 v0, 0xbfb8aa3b, v0
	v_exp_f32_e32 v156, v0
	v_lshlrev_b32_e32 v0, 16, v153
	v_mul_f32_e32 v0, 0xbfb8aa3b, v0
	v_exp_f32_e32 v0, v0
	v_pk_mul_f32 v[160:161], v[160:161], v[162:163]
	v_add_f32_e32 v0, 1.0, v0
	v_rcp_f32_e32 v152, v0
	v_and_b32_e32 v0, 0xffff0000, v157
	v_mul_f32_e32 v0, 0xbfb8aa3b, v0
	v_exp_f32_e32 v157, v0
	v_and_b32_e32 v0, 0xffff0000, v153
	v_mul_f32_e32 v0, 0xbfb8aa3b, v0
	v_exp_f32_e32 v0, v0
	v_pk_add_f32 v[156:157], v[156:157], 1.0 op_sel_hi:[1,0]
	v_pk_mul_f32 v[112:113], v[112:113], v[160:161]
	v_add_f32_e32 v0, 1.0, v0
	v_rcp_f32_e32 v153, v0
	v_lshlrev_b32_e32 v0, 16, v158
	v_mul_f32_e32 v0, 0xbfb8aa3b, v0
	v_pk_mul_f32 v[152:153], v[156:157], v[152:153]
	s_nop 0
	v_pk_mul_f32 v[114:115], v[114:115], v[152:153]
	v_exp_f32_e32 v152, v0
	v_lshlrev_b32_e32 v0, 16, v154
	v_mul_f32_e32 v0, 0xbfb8aa3b, v0
	v_exp_f32_e32 v0, v0
	s_nop 0
	v_add_f32_e32 v0, 1.0, v0
	v_rcp_f32_e32 v156, v0
	v_and_b32_e32 v0, 0xffff0000, v158
	v_mul_f32_e32 v0, 0xbfb8aa3b, v0
	v_exp_f32_e32 v153, v0
	v_and_b32_e32 v0, 0xffff0000, v154
	v_mul_f32_e32 v0, 0xbfb8aa3b, v0
	v_exp_f32_e32 v0, v0
	v_pk_add_f32 v[152:153], v[152:153], 1.0 op_sel_hi:[1,0]
	v_add_f32_e32 v0, 1.0, v0
	v_rcp_f32_e32 v157, v0
	v_lshlrev_b32_e32 v0, 16, v159
	v_mul_f32_e32 v0, 0xbfb8aa3b, v0
	v_exp_f32_e32 v158, v0
	v_lshlrev_b32_e32 v0, 16, v155
	v_mul_f32_e32 v0, 0xbfb8aa3b, v0
	v_exp_f32_e32 v0, v0
	v_pk_mul_f32 v[152:153], v[152:153], v[156:157]
	v_add_f32_e32 v0, 1.0, v0
	v_rcp_f32_e32 v154, v0
	v_and_b32_e32 v0, 0xffff0000, v159
	v_mul_f32_e32 v0, 0xbfb8aa3b, v0
	v_exp_f32_e32 v159, v0
	v_and_b32_e32 v0, 0xffff0000, v155
	v_mul_f32_e32 v0, 0xbfb8aa3b, v0
	v_exp_f32_e32 v0, v0
	v_pk_add_f32 v[158:159], v[158:159], 1.0 op_sel_hi:[1,0]
	v_pk_mul_f32 v[108:109], v[108:109], v[152:153]
	v_add_f32_e32 v0, 1.0, v0
	v_rcp_f32_e32 v155, v0
	s_nop 0
	v_pk_mul_f32 v[154:155], v[158:159], v[154:155]
	s_nop 0
	v_pk_mul_f32 v[110:111], v[110:111], v[154:155]
	s_nop 0
	s_nop 0
	s_nop 0
	s_waitcnt vmcnt(8)
	v_mov_b32_e32 v152, v204
	v_mov_b32_e32 v153, v205
	v_mov_b32_e32 v154, v206
	v_mov_b32_e32 v155, v207
	v_mov_b32_e32 v132, v208
	v_mov_b32_e32 v133, v209
	v_mov_b32_e32 v134, v210
	v_mov_b32_e32 v135, v211
	global_load_dwordx4 v[204:207], v[180:181], off
	global_load_dwordx4 v[208:211], v[182:183], off
	v_lshlrev_b32_e32 v0, 16, v132
	v_mul_f32_e32 v0, 0xbfb8aa3b, v0
	v_exp_f32_e32 v156, v0
	v_lshlrev_b32_e32 v0, 16, v152
	v_mul_f32_e32 v0, 0xbfb8aa3b, v0
	v_exp_f32_e32 v0, v0
	s_nop 0
	v_add_f32_e32 v0, 1.0, v0
	v_rcp_f32_e32 v158, v0
	v_and_b32_e32 v0, 0xffff0000, v132
	v_mul_f32_e32 v0, 0xbfb8aa3b, v0
	v_exp_f32_e32 v157, v0
	v_and_b32_e32 v0, 0xffff0000, v152
	v_mul_f32_e32 v0, 0xbfb8aa3b, v0
	v_exp_f32_e32 v0, v0
	v_pk_add_f32 v[156:157], v[156:157], 1.0 op_sel_hi:[1,0]
	v_add_f32_e32 v0, 1.0, v0
	v_rcp_f32_e32 v159, v0
	v_lshlrev_b32_e32 v0, 16, v133
	v_mul_f32_e32 v0, 0xbfb8aa3b, v0
	v_exp_f32_e32 v132, v0
	v_lshlrev_b32_e32 v0, 16, v153
	v_mul_f32_e32 v0, 0xbfb8aa3b, v0
	v_exp_f32_e32 v0, v0
	v_pk_mul_f32 v[156:157], v[156:157], v[158:159]
	v_add_f32_e32 v0, 1.0, v0
	v_rcp_f32_e32 v152, v0
	v_and_b32_e32 v0, 0xffff0000, v133
	v_mul_f32_e32 v0, 0xbfb8aa3b, v0
	v_exp_f32_e32 v133, v0
	v_and_b32_e32 v0, 0xffff0000, v153
	v_mul_f32_e32 v0, 0xbfb8aa3b, v0
	v_exp_f32_e32 v0, v0
	v_pk_add_f32 v[132:133], v[132:133], 1.0 op_sel_hi:[1,0]
	v_pk_mul_f32 v[80:81], v[80:81], v[156:157]
	v_add_f32_e32 v0, 1.0, v0
	v_rcp_f32_e32 v153, v0
	v_lshlrev_b32_e32 v0, 16, v134
	v_mul_f32_e32 v0, 0xbfb8aa3b, v0
	v_pk_mul_f32 v[132:133], v[132:133], v[152:153]
	s_nop 0
	v_pk_mul_f32 v[82:83], v[82:83], v[132:133]
	v_exp_f32_e32 v132, v0
	v_lshlrev_b32_e32 v0, 16, v154
	v_mul_f32_e32 v0, 0xbfb8aa3b, v0
	v_exp_f32_e32 v0, v0
	s_nop 0
	v_add_f32_e32 v0, 1.0, v0
	v_rcp_f32_e32 v152, v0
	v_and_b32_e32 v0, 0xffff0000, v134
	v_mul_f32_e32 v0, 0xbfb8aa3b, v0
	v_exp_f32_e32 v133, v0
	v_and_b32_e32 v0, 0xffff0000, v154
	v_mul_f32_e32 v0, 0xbfb8aa3b, v0
	v_exp_f32_e32 v0, v0
	v_pk_add_f32 v[132:133], v[132:133], 1.0 op_sel_hi:[1,0]
	v_add_f32_e32 v0, 1.0, v0
	v_rcp_f32_e32 v153, v0
	v_lshlrev_b32_e32 v0, 16, v135
	v_mul_f32_e32 v0, 0xbfb8aa3b, v0
	v_exp_f32_e32 v134, v0
	v_lshlrev_b32_e32 v0, 16, v155
	v_mul_f32_e32 v0, 0xbfb8aa3b, v0
	v_exp_f32_e32 v0, v0
	v_pk_mul_f32 v[132:133], v[132:133], v[152:153]
	v_add_f32_e32 v0, 1.0, v0
	v_rcp_f32_e32 v154, v0
	v_and_b32_e32 v0, 0xffff0000, v135
	v_mul_f32_e32 v0, 0xbfb8aa3b, v0
	v_exp_f32_e32 v135, v0
	v_and_b32_e32 v0, 0xffff0000, v155
	v_mul_f32_e32 v0, 0xbfb8aa3b, v0
	v_exp_f32_e32 v0, v0
	v_pk_mul_f32 v[76:77], v[76:77], v[132:133]
	v_lshlrev_b64 v[132:133], 10, v[138:139]
	v_pk_add_f32 v[134:135], v[134:135], 1.0 op_sel_hi:[1,0]
	v_add_f32_e32 v0, 1.0, v0
	v_rcp_f32_e32 v155, v0
	v_lshl_add_u64 v[132:133], v[132:133], 0, v[2:3]
	v_lshlrev_b64 v[132:133], 1, v[132:133]
	v_pk_mul_f32 v[134:135], v[134:135], v[154:155]
	s_nop 0
	v_pk_mul_f32 v[78:79], v[78:79], v[134:135]
	v_lshl_add_u64 v[134:135], s[2:3], 0, v[132:133]
	v_lshl_add_u64 v[132:133], s[74:75], 0, v[132:133]
	s_nop 0
	s_nop 0
	s_waitcnt vmcnt(8)
; __device__ __forceinline__ float en2(unsigned hbits) { return __builtin_amdgcn_exp2f(-1.4426950408889634f * __uint_as_float(hbits)); }
;     __device__ __forceinline__ void operator()(f32x4 (&acc)[2][2][4][2], const Unit& u, int wr, int wc, int fr, int fq) const {
;     ...
;                 for (int m = 0; m < 4; ++m) { const size_t off = (size_t)(row0 + ai * HALF + m * 16) * 1024 + col0;
; #pragma unroll
;                     for (int bj = 0; bj < 2; ++bj) { const u32x4 av = *(const u32x4*)(ga + off + bj * HALF), bv = *(const u32x4*)(gb + off + bj * HALF);
;                         const unsigned aw[4] = {av.x, av.y, av.z, av.w}, bw[4] = {bv.x, bv.y, bv.z, bv.w};
; #pragma unroll
;                         for (int q = 0; q < 4; ++q) { const int n = q >> 1, e = (q & 1) * 2;
;                             const float r0 = (1.0f + en2(bw[q] << 16)) * __builtin_amdgcn_rcpf(1.0f + en2(aw[q] << 16));
;                             const float r1 = (1.0f + en2(bw[q] & 0xffff0000u)) * __builtin_amdgcn_rcpf(1.0f + en2(aw[q] & 0xffff0000u));
;                             acc[ai][bj][m][n][e] *= r0; acc[ai][bj][m][n][e + 1] *= r1; } } }
	v_mov_b32_e32 v152, v212
	v_mov_b32_e32 v153, v213
	v_mov_b32_e32 v154, v214
	v_mov_b32_e32 v155, v215
	v_mov_b32_e32 v156, v216
	v_mov_b32_e32 v157, v217
	v_mov_b32_e32 v158, v218
	v_mov_b32_e32 v159, v219
	global_load_dwordx4 v[212:215], v[180:181], off offset:256
	global_load_dwordx4 v[216:219], v[182:183], off offset:256
	v_lshl_add_u64 v[180:181], v[180:181], 0, v[184:185]
	v_lshl_add_u64 v[182:183], v[182:183], 0, v[184:185]
	v_lshlrev_b32_e32 v0, 16, v156
	v_mul_f32_e32 v0, 0xbfb8aa3b, v0
	v_exp_f32_e32 v138, v0
	v_lshlrev_b32_e32 v0, 16, v152
	v_mul_f32_e32 v0, 0xbfb8aa3b, v0
	v_exp_f32_e32 v0, v0
	s_nop 0
	v_add_f32_e32 v0, 1.0, v0
	v_rcp_f32_e32 v160, v0
	v_and_b32_e32 v0, 0xffff0000, v156
	v_mul_f32_e32 v0, 0xbfb8aa3b, v0
	v_exp_f32_e32 v139, v0
	v_and_b32_e32 v0, 0xffff0000, v152
	v_mul_f32_e32 v0, 0xbfb8aa3b, v0
	v_exp_f32_e32 v0, v0
	v_pk_add_f32 v[138:139], v[138:139], 1.0 op_sel_hi:[1,0]
	v_add_f32_e32 v0, 1.0, v0
	v_rcp_f32_e32 v161, v0
	v_lshlrev_b32_e32 v0, 16, v157
	v_mul_f32_e32 v0, 0xbfb8aa3b, v0
	v_exp_f32_e32 v156, v0
	v_lshlrev_b32_e32 v0, 16, v153
	v_mul_f32_e32 v0, 0xbfb8aa3b, v0
	v_exp_f32_e32 v0, v0
	v_pk_mul_f32 v[138:139], v[138:139], v[160:161]
	v_add_f32_e32 v0, 1.0, v0
	v_rcp_f32_e32 v152, v0
	v_and_b32_e32 v0, 0xffff0000, v157
	v_mul_f32_e32 v0, 0xbfb8aa3b, v0
	v_exp_f32_e32 v157, v0
	v_and_b32_e32 v0, 0xffff0000, v153
	v_mul_f32_e32 v0, 0xbfb8aa3b, v0
	v_exp_f32_e32 v0, v0
	v_pk_mul_f32 v[104:105], v[104:105], v[138:139]
	v_pk_add_f32 v[156:157], v[156:157], 1.0 op_sel_hi:[1,0]
	v_add_f32_e32 v0, 1.0, v0
	v_rcp_f32_e32 v153, v0
	v_lshlrev_b32_e32 v0, 16, v158
	v_mul_f32_e32 v0, 0xbfb8aa3b, v0
	v_exp_f32_e32 v138, v0
	v_lshlrev_b32_e32 v0, 16, v154
	v_mul_f32_e32 v0, 0xbfb8aa3b, v0
	v_exp_f32_e32 v0, v0
	v_pk_mul_f32 v[152:153], v[156:157], v[152:153]
	v_add_f32_e32 v0, 1.0, v0
	v_pk_mul_f32 v[106:107], v[106:107], v[152:153]
	v_rcp_f32_e32 v152, v0
	v_and_b32_e32 v0, 0xffff0000, v158
	v_mul_f32_e32 v0, 0xbfb8aa3b, v0
	v_exp_f32_e32 v139, v0
	v_and_b32_e32 v0, 0xffff0000, v154
	v_mul_f32_e32 v0, 0xbfb8aa3b, v0
	v_exp_f32_e32 v0, v0
	v_pk_add_f32 v[138:139], v[138:139], 1.0 op_sel_hi:[1,0]
	v_add_f32_e32 v0, 1.0, v0
	v_rcp_f32_e32 v153, v0
	v_lshlrev_b32_e32 v0, 16, v159
	v_mul_f32_e32 v0, 0xbfb8aa3b, v0
	v_exp_f32_e32 v156, v0
	v_lshlrev_b32_e32 v0, 16, v155
	v_mul_f32_e32 v0, 0xbfb8aa3b, v0
	v_exp_f32_e32 v0, v0
	v_pk_mul_f32 v[138:139], v[138:139], v[152:153]
	v_add_f32_e32 v0, 1.0, v0
	v_rcp_f32_e32 v154, v0
	v_and_b32_e32 v0, 0xffff0000, v159
	v_mul_f32_e32 v0, 0xbfb8aa3b, v0
	v_exp_f32_e32 v157, v0
	v_and_b32_e32 v0, 0xffff0000, v155
	v_mul_f32_e32 v0, 0xbfb8aa3b, v0
	v_exp_f32_e32 v0, v0
	v_pk_add_f32 v[156:157], v[156:157], 1.0 op_sel_hi:[1,0]
	v_pk_mul_f32 v[100:101], v[100:101], v[138:139]
	v_add_f32_e32 v0, 1.0, v0
	v_rcp_f32_e32 v155, v0
	s_nop 0
	v_pk_mul_f32 v[152:153], v[156:157], v[154:155]
	s_nop 0
	v_pk_mul_f32 v[102:103], v[102:103], v[152:153]
	s_nop 0
	s_nop 0
	s_nop 0
	s_waitcnt vmcnt(8)
	v_mov_b32_e32 v152, v220
	v_mov_b32_e32 v153, v221
	v_mov_b32_e32 v154, v222
	v_mov_b32_e32 v155, v223
	v_mov_b32_e32 v132, v224
	v_mov_b32_e32 v133, v225
	v_mov_b32_e32 v134, v226
	v_mov_b32_e32 v135, v227
	global_load_dwordx4 v[220:223], v[180:181], off
	global_load_dwordx4 v[224:227], v[182:183], off
	v_lshlrev_b32_e32 v0, 16, v132
	v_mul_f32_e32 v0, 0xbfb8aa3b, v0
	v_exp_f32_e32 v138, v0
	v_lshlrev_b32_e32 v0, 16, v152
	v_mul_f32_e32 v0, 0xbfb8aa3b, v0
	v_exp_f32_e32 v0, v0
	s_nop 0
	v_add_f32_e32 v0, 1.0, v0
	v_rcp_f32_e32 v156, v0
	v_and_b32_e32 v0, 0xffff0000, v132
	v_mul_f32_e32 v0, 0xbfb8aa3b, v0
	v_exp_f32_e32 v139, v0
	v_and_b32_e32 v0, 0xffff0000, v152
	v_mul_f32_e32 v0, 0xbfb8aa3b, v0
	v_exp_f32_e32 v0, v0
	v_pk_add_f32 v[138:139], v[138:139], 1.0 op_sel_hi:[1,0]
	v_add_f32_e32 v0, 1.0, v0
	v_rcp_f32_e32 v157, v0
	v_lshlrev_b32_e32 v0, 16, v133
	v_mul_f32_e32 v0, 0xbfb8aa3b, v0
	v_exp_f32_e32 v132, v0
	v_lshlrev_b32_e32 v0, 16, v153
	v_mul_f32_e32 v0, 0xbfb8aa3b, v0
	v_exp_f32_e32 v0, v0
	v_pk_mul_f32 v[138:139], v[138:139], v[156:157]
	v_add_f32_e32 v0, 1.0, v0
	v_rcp_f32_e32 v152, v0
	v_and_b32_e32 v0, 0xffff0000, v133
	v_mul_f32_e32 v0, 0xbfb8aa3b, v0
	v_exp_f32_e32 v133, v0
	v_and_b32_e32 v0, 0xffff0000, v153
	v_mul_f32_e32 v0, 0xbfb8aa3b, v0
	v_exp_f32_e32 v0, v0
	v_pk_add_f32 v[132:133], v[132:133], 1.0 op_sel_hi:[1,0]
	v_pk_mul_f32 v[72:73], v[72:73], v[138:139]
	v_add_f32_e32 v0, 1.0, v0
	v_rcp_f32_e32 v153, v0
	v_lshlrev_b32_e32 v0, 16, v134
	v_mul_f32_e32 v0, 0xbfb8aa3b, v0
	v_pk_mul_f32 v[132:133], v[132:133], v[152:153]
	s_nop 0
	v_pk_mul_f32 v[74:75], v[74:75], v[132:133]
	v_exp_f32_e32 v132, v0
	v_lshlrev_b32_e32 v0, 16, v154
	v_mul_f32_e32 v0, 0xbfb8aa3b, v0
	v_exp_f32_e32 v0, v0
	s_nop 0
	v_add_f32_e32 v0, 1.0, v0
	v_rcp_f32_e32 v138, v0
	v_and_b32_e32 v0, 0xffff0000, v134
	v_mul_f32_e32 v0, 0xbfb8aa3b, v0
	v_exp_f32_e32 v133, v0
	v_and_b32_e32 v0, 0xffff0000, v154
	v_mul_f32_e32 v0, 0xbfb8aa3b, v0
	v_exp_f32_e32 v0, v0
	v_pk_add_f32 v[132:133], v[132:133], 1.0 op_sel_hi:[1,0]
	v_add_f32_e32 v0, 1.0, v0
	v_rcp_f32_e32 v139, v0
	v_lshlrev_b32_e32 v0, 16, v135
	v_mul_f32_e32 v0, 0xbfb8aa3b, v0
	v_exp_f32_e32 v134, v0
	v_lshlrev_b32_e32 v0, 16, v155
	v_mul_f32_e32 v0, 0xbfb8aa3b, v0
	v_exp_f32_e32 v0, v0
	v_pk_mul_f32 v[132:133], v[132:133], v[138:139]
	v_add_f32_e32 v0, 1.0, v0
	v_rcp_f32_e32 v152, v0
	v_and_b32_e32 v0, 0xffff0000, v135
	v_mul_f32_e32 v0, 0xbfb8aa3b, v0
	v_exp_f32_e32 v135, v0
	v_and_b32_e32 v0, 0xffff0000, v155
	v_mul_f32_e32 v0, 0xbfb8aa3b, v0
	v_exp_f32_e32 v0, v0
	v_pk_mul_f32 v[68:69], v[68:69], v[132:133]
	v_lshlrev_b64 v[132:133], 10, v[136:137]
	v_lshl_add_u64 v[2:3], v[132:133], 0, v[2:3]
	v_add_f32_e32 v0, 1.0, v0
	v_rcp_f32_e32 v153, v0
	v_pk_add_f32 v[134:135], v[134:135], 1.0 op_sel_hi:[1,0]
	v_lshlrev_b64 v[2:3], 1, v[2:3]
	v_lshl_add_u64 v[132:133], v[2:3], 0, s[54:55]
	v_pk_mul_f32 v[134:135], v[134:135], v[152:153]
	s_nop 0
	v_pk_mul_f32 v[70:71], v[70:71], v[134:135]
	v_lshl_add_u64 v[134:135], s[2:3], 0, v[132:133]
	v_lshl_add_u64 v[132:133], s[74:75], 0, v[132:133]
	s_nop 0
	s_nop 0
	s_waitcnt vmcnt(8)
; __device__ __forceinline__ float en2(unsigned hbits) { return __builtin_amdgcn_exp2f(-1.4426950408889634f * __uint_as_float(hbits)); }
;     __device__ __forceinline__ void operator()(f32x4 (&acc)[2][2][4][2], const Unit& u, int wr, int wc, int fr, int fq) const {
;     ...
;                 for (int m = 0; m < 4; ++m) { const size_t off = (size_t)(row0 + ai * HALF + m * 16) * 1024 + col0;
; #pragma unroll
;                     for (int bj = 0; bj < 2; ++bj) { const u32x4 av = *(const u32x4*)(ga + off + bj * HALF), bv = *(const u32x4*)(gb + off + bj * HALF);
;                         const unsigned aw[4] = {av.x, av.y, av.z, av.w}, bw[4] = {bv.x, bv.y, bv.z, bv.w};
; #pragma unroll
;                         for (int q = 0; q < 4; ++q) { const int n = q >> 1, e = (q & 1) * 2;
;                             const float r0 = (1.0f + en2(bw[q] << 16)) * __builtin_amdgcn_rcpf(1.0f + en2(aw[q] << 16));
;                             const float r1 = (1.0f + en2(bw[q] & 0xffff0000u)) * __builtin_amdgcn_rcpf(1.0f + en2(aw[q] & 0xffff0000u));
;                             acc[ai][bj][m][n][e] *= r0; acc[ai][bj][m][n][e + 1] *= r1; } } }
	v_mov_b32_e32 v136, v228
	v_mov_b32_e32 v137, v229
	v_mov_b32_e32 v138, v230
	v_mov_b32_e32 v139, v231
	v_mov_b32_e32 v152, v232
	v_mov_b32_e32 v153, v233
	v_mov_b32_e32 v154, v234
	v_mov_b32_e32 v155, v235
	global_load_dwordx4 v[228:231], v[180:181], off offset:256
	global_load_dwordx4 v[232:235], v[182:183], off offset:256
	v_lshl_add_u64 v[180:181], v[180:181], 0, v[184:185]
	v_lshl_add_u64 v[182:183], v[182:183], 0, v[184:185]
	v_lshlrev_b32_e32 v0, 16, v152
	v_mul_f32_e32 v0, 0xbfb8aa3b, v0
	v_exp_f32_e32 v156, v0
	v_lshlrev_b32_e32 v0, 16, v136
	v_mul_f32_e32 v0, 0xbfb8aa3b, v0
	v_exp_f32_e32 v0, v0
	s_nop 0
	v_add_f32_e32 v0, 1.0, v0
	v_rcp_f32_e32 v158, v0
	v_and_b32_e32 v0, 0xffff0000, v152
	v_mul_f32_e32 v0, 0xbfb8aa3b, v0
	v_exp_f32_e32 v157, v0
	v_and_b32_e32 v0, 0xffff0000, v136
	v_mul_f32_e32 v0, 0xbfb8aa3b, v0
	v_exp_f32_e32 v0, v0
	v_pk_add_f32 v[156:157], v[156:157], 1.0 op_sel_hi:[1,0]
	v_add_f32_e32 v0, 1.0, v0
	v_rcp_f32_e32 v159, v0
	v_lshlrev_b32_e32 v0, 16, v153
	v_mul_f32_e32 v0, 0xbfb8aa3b, v0
	v_exp_f32_e32 v152, v0
	v_lshlrev_b32_e32 v0, 16, v137
	v_mul_f32_e32 v0, 0xbfb8aa3b, v0
	v_exp_f32_e32 v0, v0
	v_pk_mul_f32 v[156:157], v[156:157], v[158:159]
	v_add_f32_e32 v0, 1.0, v0
	v_rcp_f32_e32 v136, v0
	v_and_b32_e32 v0, 0xffff0000, v153
	v_mul_f32_e32 v0, 0xbfb8aa3b, v0
	v_exp_f32_e32 v153, v0
	v_and_b32_e32 v0, 0xffff0000, v137
	v_mul_f32_e32 v0, 0xbfb8aa3b, v0
	v_exp_f32_e32 v0, v0
	v_pk_add_f32 v[152:153], v[152:153], 1.0 op_sel_hi:[1,0]
	v_pk_mul_f32 v[64:65], v[64:65], v[156:157]
	v_add_f32_e32 v0, 1.0, v0
	v_rcp_f32_e32 v137, v0
	v_lshlrev_b32_e32 v0, 16, v154
	v_mul_f32_e32 v0, 0xbfb8aa3b, v0
	v_pk_mul_f32 v[136:137], v[152:153], v[136:137]
	s_nop 0
	v_pk_mul_f32 v[66:67], v[66:67], v[136:137]
	v_exp_f32_e32 v136, v0
	v_lshlrev_b32_e32 v0, 16, v138
	v_mul_f32_e32 v0, 0xbfb8aa3b, v0
	v_exp_f32_e32 v0, v0
	s_nop 0
	v_add_f32_e32 v0, 1.0, v0
	v_rcp_f32_e32 v152, v0
	v_and_b32_e32 v0, 0xffff0000, v154
	v_mul_f32_e32 v0, 0xbfb8aa3b, v0
	v_exp_f32_e32 v137, v0
	v_and_b32_e32 v0, 0xffff0000, v138
	v_mul_f32_e32 v0, 0xbfb8aa3b, v0
	v_exp_f32_e32 v0, v0
	v_pk_add_f32 v[136:137], v[136:137], 1.0 op_sel_hi:[1,0]
	v_add_f32_e32 v0, 1.0, v0
	v_rcp_f32_e32 v153, v0
	v_lshlrev_b32_e32 v0, 16, v155
	v_mul_f32_e32 v0, 0xbfb8aa3b, v0
	v_exp_f32_e32 v154, v0
	v_lshlrev_b32_e32 v0, 16, v139
	v_mul_f32_e32 v0, 0xbfb8aa3b, v0
	v_exp_f32_e32 v0, v0
	v_pk_mul_f32 v[136:137], v[136:137], v[152:153]
	v_add_f32_e32 v0, 1.0, v0
	v_rcp_f32_e32 v138, v0
	v_and_b32_e32 v0, 0xffff0000, v155
	v_mul_f32_e32 v0, 0xbfb8aa3b, v0
	v_exp_f32_e32 v155, v0
	v_and_b32_e32 v0, 0xffff0000, v139
	v_mul_f32_e32 v0, 0xbfb8aa3b, v0
	v_exp_f32_e32 v0, v0
	v_pk_add_f32 v[154:155], v[154:155], 1.0 op_sel_hi:[1,0]
	v_pk_mul_f32 v[60:61], v[60:61], v[136:137]
	v_add_f32_e32 v0, 1.0, v0
	v_rcp_f32_e32 v139, v0
	s_nop 0
	v_pk_mul_f32 v[138:139], v[154:155], v[138:139]
	s_nop 0
	s_nop 0
	s_nop 0
	v_pk_mul_f32 v[62:63], v[62:63], v[138:139]
	s_waitcnt vmcnt(8)
	v_mov_b32_e32 v134, v236
	v_mov_b32_e32 v135, v237
	v_mov_b32_e32 v136, v238
	v_mov_b32_e32 v137, v239
	v_mov_b32_e32 v152, v240
	v_mov_b32_e32 v153, v241
	v_mov_b32_e32 v154, v242
	v_mov_b32_e32 v155, v243
	global_load_dwordx4 v[236:239], v[180:181], off
	global_load_dwordx4 v[240:243], v[182:183], off
	v_lshlrev_b32_e32 v0, 16, v152
	v_mul_f32_e32 v0, 0xbfb8aa3b, v0
	v_exp_f32_e32 v132, v0
	v_lshlrev_b32_e32 v0, 16, v134
	v_mul_f32_e32 v0, 0xbfb8aa3b, v0
	v_exp_f32_e32 v0, v0
	s_nop 0
	v_add_f32_e32 v0, 1.0, v0
	v_rcp_f32_e32 v138, v0
	v_and_b32_e32 v0, 0xffff0000, v152
	v_mul_f32_e32 v0, 0xbfb8aa3b, v0
	v_exp_f32_e32 v133, v0
	v_and_b32_e32 v0, 0xffff0000, v134
	v_mul_f32_e32 v0, 0xbfb8aa3b, v0
	v_exp_f32_e32 v0, v0
	v_pk_add_f32 v[132:133], v[132:133], 1.0 op_sel_hi:[1,0]
	v_add_f32_e32 v0, 1.0, v0
	v_rcp_f32_e32 v139, v0
	v_lshlrev_b32_e32 v0, 16, v153
	v_mul_f32_e32 v0, 0xbfb8aa3b, v0
	v_exp_f32_e32 v152, v0
	v_lshlrev_b32_e32 v0, 16, v135
	v_mul_f32_e32 v0, 0xbfb8aa3b, v0
	v_exp_f32_e32 v0, v0
	v_pk_mul_f32 v[132:133], v[132:133], v[138:139]
	v_add_f32_e32 v0, 1.0, v0
	v_rcp_f32_e32 v134, v0
	v_and_b32_e32 v0, 0xffff0000, v153
	v_mul_f32_e32 v0, 0xbfb8aa3b, v0
	v_exp_f32_e32 v153, v0
	v_and_b32_e32 v0, 0xffff0000, v135
	v_mul_f32_e32 v0, 0xbfb8aa3b, v0
	v_exp_f32_e32 v0, v0
	v_pk_mul_f32 v[32:33], v[32:33], v[132:133]
	v_pk_add_f32 v[152:153], v[152:153], 1.0 op_sel_hi:[1,0]
	v_add_f32_e32 v0, 1.0, v0
	v_rcp_f32_e32 v135, v0
	v_lshlrev_b32_e32 v0, 16, v154
	v_mul_f32_e32 v0, 0xbfb8aa3b, v0
	v_exp_f32_e32 v132, v0
	v_lshlrev_b32_e32 v0, 16, v136
	v_mul_f32_e32 v0, 0xbfb8aa3b, v0
	v_exp_f32_e32 v0, v0
	v_pk_mul_f32 v[134:135], v[152:153], v[134:135]
	v_add_f32_e32 v0, 1.0, v0
	v_pk_mul_f32 v[34:35], v[34:35], v[134:135]
	v_rcp_f32_e32 v134, v0
	v_and_b32_e32 v0, 0xffff0000, v154
	v_mul_f32_e32 v0, 0xbfb8aa3b, v0
	v_exp_f32_e32 v133, v0
	v_and_b32_e32 v0, 0xffff0000, v136
	v_mul_f32_e32 v0, 0xbfb8aa3b, v0
	v_exp_f32_e32 v0, v0
	v_pk_add_f32 v[132:133], v[132:133], 1.0 op_sel_hi:[1,0]
	v_add_f32_e32 v0, 1.0, v0
	v_rcp_f32_e32 v135, v0
	v_lshlrev_b32_e32 v0, 16, v155
	v_mul_f32_e32 v0, 0xbfb8aa3b, v0
	v_exp_f32_e32 v138, v0
	v_lshlrev_b32_e32 v0, 16, v137
	v_mul_f32_e32 v0, 0xbfb8aa3b, v0
	v_exp_f32_e32 v0, v0
	v_pk_mul_f32 v[132:133], v[132:133], v[134:135]
	v_add_f32_e32 v0, 1.0, v0
	v_rcp_f32_e32 v136, v0
	v_and_b32_e32 v0, 0xffff0000, v155
	v_mul_f32_e32 v0, 0xbfb8aa3b, v0
	v_exp_f32_e32 v139, v0
	v_and_b32_e32 v0, 0xffff0000, v137
	v_mul_f32_e32 v0, 0xbfb8aa3b, v0
	v_exp_f32_e32 v0, v0
	v_pk_add_f32 v[138:139], v[138:139], 1.0 op_sel_hi:[1,0]
	v_pk_mul_f32 v[28:29], v[28:29], v[132:133]
	v_lshl_add_u64 v[132:133], v[2:3], 0, s[18:19]
	v_add_f32_e32 v0, 1.0, v0
	v_rcp_f32_e32 v137, v0
	s_mov_b64 s[18:19], 0x50000
	v_pk_mul_f32 v[134:135], v[138:139], v[136:137]
	s_nop 0
	v_pk_mul_f32 v[30:31], v[30:31], v[134:135]
	v_lshl_add_u64 v[134:135], s[2:3], 0, v[132:133]
	v_lshl_add_u64 v[132:133], s[74:75], 0, v[132:133]
	s_nop 0
	s_nop 0
	s_waitcnt vmcnt(8)
; __device__ __forceinline__ float en2(unsigned hbits) { return __builtin_amdgcn_exp2f(-1.4426950408889634f * __uint_as_float(hbits)); }
;     __device__ __forceinline__ void operator()(f32x4 (&acc)[2][2][4][2], const Unit& u, int wr, int wc, int fr, int fq) const {
;     ...
;                 for (int m = 0; m < 4; ++m) { const size_t off = (size_t)(row0 + ai * HALF + m * 16) * 1024 + col0;
; #pragma unroll
;                     for (int bj = 0; bj < 2; ++bj) { const u32x4 av = *(const u32x4*)(ga + off + bj * HALF), bv = *(const u32x4*)(gb + off + bj * HALF);
;                         const unsigned aw[4] = {av.x, av.y, av.z, av.w}, bw[4] = {bv.x, bv.y, bv.z, bv.w};
; #pragma unroll
;                         for (int q = 0; q < 4; ++q) { const int n = q >> 1, e = (q & 1) * 2;
;                             const float r0 = (1.0f + en2(bw[q] << 16)) * __builtin_amdgcn_rcpf(1.0f + en2(aw[q] << 16));
;                             const float r1 = (1.0f + en2(bw[q] & 0xffff0000u)) * __builtin_amdgcn_rcpf(1.0f + en2(aw[q] & 0xffff0000u));
;                             acc[ai][bj][m][n][e] *= r0; acc[ai][bj][m][n][e + 1] *= r1; } } }
	v_mov_b32_e32 v136, v204
	v_mov_b32_e32 v137, v205
	v_mov_b32_e32 v138, v206
	v_mov_b32_e32 v139, v207
	v_mov_b32_e32 v152, v208
	v_mov_b32_e32 v153, v209
	v_mov_b32_e32 v154, v210
	v_mov_b32_e32 v155, v211
	global_load_dwordx4 v[204:207], v[180:181], off offset:256
	global_load_dwordx4 v[208:211], v[182:183], off offset:256
	v_lshlrev_b32_e32 v0, 16, v152
	v_mul_f32_e32 v0, 0xbfb8aa3b, v0
	v_exp_f32_e32 v156, v0
	v_lshlrev_b32_e32 v0, 16, v136
	v_mul_f32_e32 v0, 0xbfb8aa3b, v0
	v_exp_f32_e32 v0, v0
	s_nop 0
	v_add_f32_e32 v0, 1.0, v0
	v_rcp_f32_e32 v158, v0
	v_and_b32_e32 v0, 0xffff0000, v152
	v_mul_f32_e32 v0, 0xbfb8aa3b, v0
	v_exp_f32_e32 v157, v0
	v_and_b32_e32 v0, 0xffff0000, v136
	v_mul_f32_e32 v0, 0xbfb8aa3b, v0
	v_exp_f32_e32 v0, v0
	v_pk_add_f32 v[156:157], v[156:157], 1.0 op_sel_hi:[1,0]
	v_add_f32_e32 v0, 1.0, v0
	v_rcp_f32_e32 v159, v0
	v_lshlrev_b32_e32 v0, 16, v153
	v_mul_f32_e32 v0, 0xbfb8aa3b, v0
	v_exp_f32_e32 v152, v0
	v_lshlrev_b32_e32 v0, 16, v137
	v_mul_f32_e32 v0, 0xbfb8aa3b, v0
	v_exp_f32_e32 v0, v0
	v_pk_mul_f32 v[156:157], v[156:157], v[158:159]
	v_add_f32_e32 v0, 1.0, v0
	v_rcp_f32_e32 v136, v0
	v_and_b32_e32 v0, 0xffff0000, v153
	v_mul_f32_e32 v0, 0xbfb8aa3b, v0
	v_exp_f32_e32 v153, v0
	v_and_b32_e32 v0, 0xffff0000, v137
	v_mul_f32_e32 v0, 0xbfb8aa3b, v0
	v_exp_f32_e32 v0, v0
	v_pk_add_f32 v[152:153], v[152:153], 1.0 op_sel_hi:[1,0]
	v_pk_mul_f32 v[56:57], v[56:57], v[156:157]
	v_add_f32_e32 v0, 1.0, v0
	v_rcp_f32_e32 v137, v0
	v_lshlrev_b32_e32 v0, 16, v154
	v_mul_f32_e32 v0, 0xbfb8aa3b, v0
	v_pk_mul_f32 v[136:137], v[152:153], v[136:137]
	s_nop 0
	v_pk_mul_f32 v[58:59], v[58:59], v[136:137]
	v_exp_f32_e32 v136, v0
	v_lshlrev_b32_e32 v0, 16, v138
	v_mul_f32_e32 v0, 0xbfb8aa3b, v0
	v_exp_f32_e32 v0, v0
	s_nop 0
	v_add_f32_e32 v0, 1.0, v0
	v_rcp_f32_e32 v152, v0
	v_and_b32_e32 v0, 0xffff0000, v154
	v_mul_f32_e32 v0, 0xbfb8aa3b, v0
	v_exp_f32_e32 v137, v0
	v_and_b32_e32 v0, 0xffff0000, v138
	v_mul_f32_e32 v0, 0xbfb8aa3b, v0
	v_exp_f32_e32 v0, v0
	v_pk_add_f32 v[136:137], v[136:137], 1.0 op_sel_hi:[1,0]
	v_add_f32_e32 v0, 1.0, v0
	v_rcp_f32_e32 v153, v0
	v_lshlrev_b32_e32 v0, 16, v155
	v_mul_f32_e32 v0, 0xbfb8aa3b, v0
	v_exp_f32_e32 v154, v0
	v_lshlrev_b32_e32 v0, 16, v139
	v_mul_f32_e32 v0, 0xbfb8aa3b, v0
	v_exp_f32_e32 v0, v0
	v_pk_mul_f32 v[136:137], v[136:137], v[152:153]
	v_add_f32_e32 v0, 1.0, v0
	v_rcp_f32_e32 v138, v0
	v_and_b32_e32 v0, 0xffff0000, v155
	v_mul_f32_e32 v0, 0xbfb8aa3b, v0
	v_exp_f32_e32 v155, v0
	v_and_b32_e32 v0, 0xffff0000, v139
	v_mul_f32_e32 v0, 0xbfb8aa3b, v0
	v_exp_f32_e32 v0, v0
	v_pk_add_f32 v[154:155], v[154:155], 1.0 op_sel_hi:[1,0]
	v_pk_mul_f32 v[52:53], v[52:53], v[136:137]
	v_add_f32_e32 v0, 1.0, v0
	v_rcp_f32_e32 v139, v0
	s_nop 0
	v_pk_mul_f32 v[138:139], v[154:155], v[138:139]
	s_nop 0
	s_nop 0
	s_nop 0
	v_pk_mul_f32 v[54:55], v[54:55], v[138:139]
	s_waitcnt vmcnt(8)
	v_mov_b32_e32 v134, v212
	v_mov_b32_e32 v135, v213
	v_mov_b32_e32 v136, v214
	v_mov_b32_e32 v137, v215
	v_mov_b32_e32 v152, v216
	v_mov_b32_e32 v153, v217
	v_mov_b32_e32 v154, v218
	v_mov_b32_e32 v155, v219
	v_lshlrev_b32_e32 v0, 16, v152
	v_mul_f32_e32 v0, 0xbfb8aa3b, v0
	v_exp_f32_e32 v132, v0
	v_lshlrev_b32_e32 v0, 16, v134
	v_mul_f32_e32 v0, 0xbfb8aa3b, v0
	v_exp_f32_e32 v0, v0
	s_nop 0
	v_add_f32_e32 v0, 1.0, v0
	v_rcp_f32_e32 v138, v0
	v_and_b32_e32 v0, 0xffff0000, v152
	v_mul_f32_e32 v0, 0xbfb8aa3b, v0
	v_exp_f32_e32 v133, v0
	v_and_b32_e32 v0, 0xffff0000, v134
	v_mul_f32_e32 v0, 0xbfb8aa3b, v0
	v_exp_f32_e32 v0, v0
	v_pk_add_f32 v[132:133], v[132:133], 1.0 op_sel_hi:[1,0]
	v_add_f32_e32 v0, 1.0, v0
	v_rcp_f32_e32 v139, v0
	v_lshlrev_b32_e32 v0, 16, v153
	v_mul_f32_e32 v0, 0xbfb8aa3b, v0
	v_exp_f32_e32 v152, v0
	v_lshlrev_b32_e32 v0, 16, v135
	v_mul_f32_e32 v0, 0xbfb8aa3b, v0
	v_exp_f32_e32 v0, v0
	v_pk_mul_f32 v[132:133], v[132:133], v[138:139]
	v_add_f32_e32 v0, 1.0, v0
	v_rcp_f32_e32 v134, v0
	v_and_b32_e32 v0, 0xffff0000, v153
	v_mul_f32_e32 v0, 0xbfb8aa3b, v0
	v_exp_f32_e32 v153, v0
	v_and_b32_e32 v0, 0xffff0000, v135
	v_mul_f32_e32 v0, 0xbfb8aa3b, v0
	v_exp_f32_e32 v0, v0
	v_pk_mul_f32 v[24:25], v[24:25], v[132:133]
	v_pk_add_f32 v[152:153], v[152:153], 1.0 op_sel_hi:[1,0]
	v_add_f32_e32 v0, 1.0, v0
	v_rcp_f32_e32 v135, v0
	v_lshlrev_b32_e32 v0, 16, v154
	v_mul_f32_e32 v0, 0xbfb8aa3b, v0
	v_exp_f32_e32 v132, v0
	v_lshlrev_b32_e32 v0, 16, v136
	v_mul_f32_e32 v0, 0xbfb8aa3b, v0
	v_exp_f32_e32 v0, v0
	v_pk_mul_f32 v[134:135], v[152:153], v[134:135]
	v_add_f32_e32 v0, 1.0, v0
	v_pk_mul_f32 v[26:27], v[26:27], v[134:135]
	v_rcp_f32_e32 v134, v0
	v_and_b32_e32 v0, 0xffff0000, v154
	v_mul_f32_e32 v0, 0xbfb8aa3b, v0
	v_exp_f32_e32 v133, v0
	v_and_b32_e32 v0, 0xffff0000, v136
	v_mul_f32_e32 v0, 0xbfb8aa3b, v0
	v_exp_f32_e32 v0, v0
	v_pk_add_f32 v[132:133], v[132:133], 1.0 op_sel_hi:[1,0]
	v_add_f32_e32 v0, 1.0, v0
	v_rcp_f32_e32 v135, v0
	v_lshlrev_b32_e32 v0, 16, v155
	v_mul_f32_e32 v0, 0xbfb8aa3b, v0
	v_exp_f32_e32 v138, v0
	v_lshlrev_b32_e32 v0, 16, v137
	v_mul_f32_e32 v0, 0xbfb8aa3b, v0
	v_exp_f32_e32 v0, v0
	v_pk_mul_f32 v[132:133], v[132:133], v[134:135]
	v_add_f32_e32 v0, 1.0, v0
	v_rcp_f32_e32 v136, v0
	v_and_b32_e32 v0, 0xffff0000, v155
	v_mul_f32_e32 v0, 0xbfb8aa3b, v0
	v_exp_f32_e32 v139, v0
	v_and_b32_e32 v0, 0xffff0000, v137
	v_mul_f32_e32 v0, 0xbfb8aa3b, v0
	v_exp_f32_e32 v0, v0
	v_pk_add_f32 v[138:139], v[138:139], 1.0 op_sel_hi:[1,0]
	v_pk_mul_f32 v[20:21], v[20:21], v[132:133]
	v_add_f32_e32 v0, 1.0, v0
	v_rcp_f32_e32 v137, v0
	s_nop 0
	v_pk_mul_f32 v[134:135], v[138:139], v[136:137]
	s_nop 0
	v_pk_mul_f32 v[22:23], v[22:23], v[134:135]
	v_lshl_add_u64 v[134:135], v[2:3], 0, s[18:19]
	v_lshl_add_u64 v[132:133], s[2:3], 0, v[134:135]
	v_lshl_add_u64 v[136:137], s[74:75], 0, v[134:135]
	s_nop 0
	s_nop 0
	s_mov_b64 s[18:19], 0x58000
	v_lshl_add_u64 v[2:3], v[2:3], 0, s[18:19]
	s_waitcnt vmcnt(6)
; __device__ __forceinline__ float en2(unsigned hbits) { return __builtin_amdgcn_exp2f(-1.4426950408889634f * __uint_as_float(hbits)); }
;     __device__ __forceinline__ void operator()(f32x4 (&acc)[2][2][4][2], const Unit& u, int wr, int wc, int fr, int fq) const {
;     ...
;                 for (int m = 0; m < 4; ++m) { const size_t off = (size_t)(row0 + ai * HALF + m * 16) * 1024 + col0;
; #pragma unroll
;                     for (int bj = 0; bj < 2; ++bj) { const u32x4 av = *(const u32x4*)(ga + off + bj * HALF), bv = *(const u32x4*)(gb + off + bj * HALF);
;                         const unsigned aw[4] = {av.x, av.y, av.z, av.w}, bw[4] = {bv.x, bv.y, bv.z, bv.w};
; #pragma unroll
;                         for (int q = 0; q < 4; ++q) { const int n = q >> 1, e = (q & 1) * 2;
;                             const float r0 = (1.0f + en2(bw[q] << 16)) * __builtin_amdgcn_rcpf(1.0f + en2(aw[q] << 16));
;                             const float r1 = (1.0f + en2(bw[q] & 0xffff0000u)) * __builtin_amdgcn_rcpf(1.0f + en2(aw[q] & 0xffff0000u));
;                             acc[ai][bj][m][n][e] *= r0; acc[ai][bj][m][n][e + 1] *= r1; } } }
	v_mov_b32_e32 v152, v220
	v_mov_b32_e32 v153, v221
	v_mov_b32_e32 v154, v222
	v_mov_b32_e32 v155, v223
	v_mov_b32_e32 v156, v224
	v_mov_b32_e32 v157, v225
	v_mov_b32_e32 v158, v226
	v_mov_b32_e32 v159, v227
	v_lshlrev_b32_e32 v0, 16, v156
	v_mul_f32_e32 v0, 0xbfb8aa3b, v0
	v_exp_f32_e32 v134, v0
	v_lshlrev_b32_e32 v0, 16, v152
	v_mul_f32_e32 v0, 0xbfb8aa3b, v0
	v_exp_f32_e32 v0, v0
	s_nop 0
	v_add_f32_e32 v0, 1.0, v0
	v_rcp_f32_e32 v138, v0
	v_and_b32_e32 v0, 0xffff0000, v156
	v_mul_f32_e32 v0, 0xbfb8aa3b, v0
	v_exp_f32_e32 v135, v0
	v_and_b32_e32 v0, 0xffff0000, v152
	v_mul_f32_e32 v0, 0xbfb8aa3b, v0
	v_exp_f32_e32 v0, v0
	v_pk_add_f32 v[134:135], v[134:135], 1.0 op_sel_hi:[1,0]
	v_add_f32_e32 v0, 1.0, v0
	v_rcp_f32_e32 v139, v0
	v_lshlrev_b32_e32 v0, 16, v157
	v_mul_f32_e32 v0, 0xbfb8aa3b, v0
	v_exp_f32_e32 v156, v0
	v_lshlrev_b32_e32 v0, 16, v153
	v_mul_f32_e32 v0, 0xbfb8aa3b, v0
	v_exp_f32_e32 v0, v0
	v_pk_mul_f32 v[134:135], v[134:135], v[138:139]
	v_add_f32_e32 v0, 1.0, v0
	v_rcp_f32_e32 v152, v0
	v_and_b32_e32 v0, 0xffff0000, v157
	v_mul_f32_e32 v0, 0xbfb8aa3b, v0
	v_exp_f32_e32 v157, v0
	v_and_b32_e32 v0, 0xffff0000, v153
	v_mul_f32_e32 v0, 0xbfb8aa3b, v0
	v_exp_f32_e32 v0, v0
	v_pk_mul_f32 v[48:49], v[48:49], v[134:135]
	v_pk_add_f32 v[156:157], v[156:157], 1.0 op_sel_hi:[1,0]
	v_add_f32_e32 v0, 1.0, v0
	v_rcp_f32_e32 v153, v0
	v_lshlrev_b32_e32 v0, 16, v158
	v_mul_f32_e32 v0, 0xbfb8aa3b, v0
	v_exp_f32_e32 v134, v0
	v_lshlrev_b32_e32 v0, 16, v154
	v_mul_f32_e32 v0, 0xbfb8aa3b, v0
	v_exp_f32_e32 v0, v0
	v_pk_mul_f32 v[138:139], v[156:157], v[152:153]
	v_add_f32_e32 v0, 1.0, v0
	v_pk_mul_f32 v[50:51], v[50:51], v[138:139]
	v_rcp_f32_e32 v138, v0
	v_and_b32_e32 v0, 0xffff0000, v158
	v_mul_f32_e32 v0, 0xbfb8aa3b, v0
	v_exp_f32_e32 v135, v0
	v_and_b32_e32 v0, 0xffff0000, v154
	v_mul_f32_e32 v0, 0xbfb8aa3b, v0
	v_exp_f32_e32 v0, v0
	v_pk_add_f32 v[134:135], v[134:135], 1.0 op_sel_hi:[1,0]
	v_add_f32_e32 v0, 1.0, v0
	v_rcp_f32_e32 v139, v0
	v_lshlrev_b32_e32 v0, 16, v159
	v_mul_f32_e32 v0, 0xbfb8aa3b, v0
	v_exp_f32_e32 v152, v0
	v_lshlrev_b32_e32 v0, 16, v155
	v_mul_f32_e32 v0, 0xbfb8aa3b, v0
	v_exp_f32_e32 v0, v0
	v_pk_mul_f32 v[134:135], v[134:135], v[138:139]
	v_add_f32_e32 v0, 1.0, v0
	v_rcp_f32_e32 v154, v0
	v_and_b32_e32 v0, 0xffff0000, v159
	v_mul_f32_e32 v0, 0xbfb8aa3b, v0
	v_exp_f32_e32 v153, v0
	v_and_b32_e32 v0, 0xffff0000, v155
	v_mul_f32_e32 v0, 0xbfb8aa3b, v0
	v_exp_f32_e32 v0, v0
	v_pk_add_f32 v[152:153], v[152:153], 1.0 op_sel_hi:[1,0]
	v_pk_mul_f32 v[44:45], v[44:45], v[134:135]
	v_add_f32_e32 v0, 1.0, v0
	v_rcp_f32_e32 v155, v0
	s_nop 0
	v_pk_mul_f32 v[138:139], v[152:153], v[154:155]
	s_nop 0
	v_pk_mul_f32 v[46:47], v[46:47], v[138:139]
	s_nop 0
	s_nop 0
	s_nop 0
	s_waitcnt vmcnt(4)
	v_mov_b32_e32 v132, v228
	v_mov_b32_e32 v133, v229
	v_mov_b32_e32 v134, v230
	v_mov_b32_e32 v135, v231
	v_mov_b32_e32 v136, v232
	v_mov_b32_e32 v137, v233
	v_mov_b32_e32 v138, v234
	v_mov_b32_e32 v139, v235
	v_lshlrev_b32_e32 v0, 16, v136
	v_mul_f32_e32 v0, 0xbfb8aa3b, v0
	v_exp_f32_e32 v152, v0
	v_lshlrev_b32_e32 v0, 16, v132
	v_mul_f32_e32 v0, 0xbfb8aa3b, v0
	v_exp_f32_e32 v0, v0
	s_nop 0
	v_add_f32_e32 v0, 1.0, v0
	v_rcp_f32_e32 v154, v0
	v_and_b32_e32 v0, 0xffff0000, v136
	v_mul_f32_e32 v0, 0xbfb8aa3b, v0
	v_exp_f32_e32 v153, v0
	v_and_b32_e32 v0, 0xffff0000, v132
	v_mul_f32_e32 v0, 0xbfb8aa3b, v0
	v_exp_f32_e32 v0, v0
	v_pk_add_f32 v[152:153], v[152:153], 1.0 op_sel_hi:[1,0]
	v_add_f32_e32 v0, 1.0, v0
	v_rcp_f32_e32 v155, v0
	v_lshlrev_b32_e32 v0, 16, v137
	v_mul_f32_e32 v0, 0xbfb8aa3b, v0
	v_exp_f32_e32 v136, v0
	v_lshlrev_b32_e32 v0, 16, v133
	v_mul_f32_e32 v0, 0xbfb8aa3b, v0
	v_exp_f32_e32 v0, v0
	v_pk_mul_f32 v[152:153], v[152:153], v[154:155]
	v_add_f32_e32 v0, 1.0, v0
	v_rcp_f32_e32 v132, v0
	v_and_b32_e32 v0, 0xffff0000, v137
	v_mul_f32_e32 v0, 0xbfb8aa3b, v0
	v_exp_f32_e32 v137, v0
	v_and_b32_e32 v0, 0xffff0000, v133
	v_mul_f32_e32 v0, 0xbfb8aa3b, v0
	v_exp_f32_e32 v0, v0
	v_pk_add_f32 v[136:137], v[136:137], 1.0 op_sel_hi:[1,0]
	v_pk_mul_f32 v[16:17], v[16:17], v[152:153]
	v_add_f32_e32 v0, 1.0, v0
	v_rcp_f32_e32 v133, v0
	v_lshlrev_b32_e32 v0, 16, v138
	v_mul_f32_e32 v0, 0xbfb8aa3b, v0
	v_pk_mul_f32 v[132:133], v[136:137], v[132:133]
	s_nop 0
	v_pk_mul_f32 v[18:19], v[18:19], v[132:133]
	v_exp_f32_e32 v132, v0
	v_lshlrev_b32_e32 v0, 16, v134
	v_mul_f32_e32 v0, 0xbfb8aa3b, v0
	v_exp_f32_e32 v0, v0
	s_nop 0
	v_add_f32_e32 v0, 1.0, v0
	v_rcp_f32_e32 v136, v0
	v_and_b32_e32 v0, 0xffff0000, v138
	v_mul_f32_e32 v0, 0xbfb8aa3b, v0
	v_exp_f32_e32 v133, v0
	v_and_b32_e32 v0, 0xffff0000, v134
	v_mul_f32_e32 v0, 0xbfb8aa3b, v0
	v_exp_f32_e32 v0, v0
	v_pk_add_f32 v[132:133], v[132:133], 1.0 op_sel_hi:[1,0]
	v_add_f32_e32 v0, 1.0, v0
	v_rcp_f32_e32 v137, v0
	v_lshlrev_b32_e32 v0, 16, v139
	v_mul_f32_e32 v0, 0xbfb8aa3b, v0
	v_exp_f32_e32 v138, v0
	v_lshlrev_b32_e32 v0, 16, v135
	v_mul_f32_e32 v0, 0xbfb8aa3b, v0
	v_exp_f32_e32 v0, v0
	v_pk_mul_f32 v[132:133], v[132:133], v[136:137]
	v_add_f32_e32 v0, 1.0, v0
	v_rcp_f32_e32 v134, v0
	v_and_b32_e32 v0, 0xffff0000, v139
	v_mul_f32_e32 v0, 0xbfb8aa3b, v0
	v_exp_f32_e32 v139, v0
	v_and_b32_e32 v0, 0xffff0000, v135
	v_mul_f32_e32 v0, 0xbfb8aa3b, v0
	v_exp_f32_e32 v0, v0
	v_pk_add_f32 v[138:139], v[138:139], 1.0 op_sel_hi:[1,0]
	v_pk_mul_f32 v[12:13], v[12:13], v[132:133]
	v_lshl_add_u64 v[132:133], s[2:3], 0, v[2:3]
	v_add_f32_e32 v0, 1.0, v0
	v_rcp_f32_e32 v135, v0
	v_lshl_add_u64 v[2:3], s[74:75], 0, v[2:3]
	s_nop 0
	v_pk_mul_f32 v[134:135], v[138:139], v[134:135]
	s_nop 0
	v_pk_mul_f32 v[14:15], v[14:15], v[134:135]
	s_nop 0
	s_waitcnt vmcnt(2)
; __device__ __forceinline__ float en2(unsigned hbits) { return __builtin_amdgcn_exp2f(-1.4426950408889634f * __uint_as_float(hbits)); }
;     __device__ __forceinline__ void operator()(f32x4 (&acc)[2][2][4][2], const Unit& u, int wr, int wc, int fr, int fq) const {
;     ...
;                 for (int m = 0; m < 4; ++m) { const size_t off = (size_t)(row0 + ai * HALF + m * 16) * 1024 + col0;
; #pragma unroll
;                     for (int bj = 0; bj < 2; ++bj) { const u32x4 av = *(const u32x4*)(ga + off + bj * HALF), bv = *(const u32x4*)(gb + off + bj * HALF);
;                         const unsigned aw[4] = {av.x, av.y, av.z, av.w}, bw[4] = {bv.x, bv.y, bv.z, bv.w};
; #pragma unroll
;                         for (int q = 0; q < 4; ++q) { const int n = q >> 1, e = (q & 1) * 2;
;                             const float r0 = (1.0f + en2(bw[q] << 16)) * __builtin_amdgcn_rcpf(1.0f + en2(aw[q] << 16));
;                             const float r1 = (1.0f + en2(bw[q] & 0xffff0000u)) * __builtin_amdgcn_rcpf(1.0f + en2(aw[q] & 0xffff0000u));
;                             acc[ai][bj][m][n][e] *= r0; acc[ai][bj][m][n][e + 1] *= r1; } } }
	v_mov_b32_e32 v152, v240
	v_mov_b32_e32 v153, v241
	v_mov_b32_e32 v154, v242
	v_mov_b32_e32 v155, v243
	v_mov_b32_e32 v134, v236
	v_mov_b32_e32 v135, v237
	v_mov_b32_e32 v136, v238
	v_mov_b32_e32 v137, v239
	v_lshlrev_b32_e32 v0, 16, v152
	v_mul_f32_e32 v0, 0xbfb8aa3b, v0
	v_exp_f32_e32 v138, v0
	s_nop 0
	v_lshlrev_b32_e32 v0, 16, v134
	v_mul_f32_e32 v0, 0xbfb8aa3b, v0
	v_exp_f32_e32 v0, v0
	s_nop 0
	v_add_f32_e32 v0, 1.0, v0
	v_rcp_f32_e32 v156, v0
	v_and_b32_e32 v0, 0xffff0000, v152
	v_mul_f32_e32 v0, 0xbfb8aa3b, v0
	v_exp_f32_e32 v139, v0
	v_and_b32_e32 v0, 0xffff0000, v134
	v_mul_f32_e32 v0, 0xbfb8aa3b, v0
	v_exp_f32_e32 v0, v0
	v_pk_add_f32 v[138:139], v[138:139], 1.0 op_sel_hi:[1,0]
	v_add_f32_e32 v0, 1.0, v0
	v_rcp_f32_e32 v157, v0
	v_lshlrev_b32_e32 v0, 16, v153
	v_mul_f32_e32 v0, 0xbfb8aa3b, v0
	v_exp_f32_e32 v152, v0
	v_lshlrev_b32_e32 v0, 16, v135
	v_mul_f32_e32 v0, 0xbfb8aa3b, v0
	v_exp_f32_e32 v0, v0
	v_pk_mul_f32 v[138:139], v[138:139], v[156:157]
	v_add_f32_e32 v0, 1.0, v0
	v_rcp_f32_e32 v134, v0
	v_and_b32_e32 v0, 0xffff0000, v153
	v_mul_f32_e32 v0, 0xbfb8aa3b, v0
	v_exp_f32_e32 v153, v0
	v_and_b32_e32 v0, 0xffff0000, v135
	v_mul_f32_e32 v0, 0xbfb8aa3b, v0
	v_exp_f32_e32 v0, v0
	v_pk_add_f32 v[152:153], v[152:153], 1.0 op_sel_hi:[1,0]
	v_pk_mul_f32 v[40:41], v[40:41], v[138:139]
	v_add_f32_e32 v0, 1.0, v0
	v_rcp_f32_e32 v135, v0
	v_lshlrev_b32_e32 v0, 16, v154
	v_mul_f32_e32 v0, 0xbfb8aa3b, v0
	v_pk_mul_f32 v[134:135], v[152:153], v[134:135]
	s_nop 0
	v_pk_mul_f32 v[42:43], v[42:43], v[134:135]
	v_exp_f32_e32 v134, v0
	v_lshlrev_b32_e32 v0, 16, v136
	v_mul_f32_e32 v0, 0xbfb8aa3b, v0
	v_exp_f32_e32 v0, v0
	s_nop 0
	v_add_f32_e32 v0, 1.0, v0
	v_rcp_f32_e32 v138, v0
	v_and_b32_e32 v0, 0xffff0000, v154
	v_mul_f32_e32 v0, 0xbfb8aa3b, v0
	v_exp_f32_e32 v135, v0
	v_and_b32_e32 v0, 0xffff0000, v136
	v_mul_f32_e32 v0, 0xbfb8aa3b, v0
	v_exp_f32_e32 v0, v0
	v_pk_add_f32 v[134:135], v[134:135], 1.0 op_sel_hi:[1,0]
	v_add_f32_e32 v0, 1.0, v0
	v_rcp_f32_e32 v139, v0
	v_lshlrev_b32_e32 v0, 16, v155
	v_mul_f32_e32 v0, 0xbfb8aa3b, v0
	v_exp_f32_e32 v152, v0
	v_lshlrev_b32_e32 v0, 16, v137
	v_mul_f32_e32 v0, 0xbfb8aa3b, v0
	v_exp_f32_e32 v0, v0
	v_pk_mul_f32 v[134:135], v[134:135], v[138:139]
	v_add_f32_e32 v0, 1.0, v0
	v_rcp_f32_e32 v136, v0
	v_and_b32_e32 v0, 0xffff0000, v155
	v_mul_f32_e32 v0, 0xbfb8aa3b, v0
	v_exp_f32_e32 v153, v0
	v_and_b32_e32 v0, 0xffff0000, v137
	v_mul_f32_e32 v0, 0xbfb8aa3b, v0
	v_exp_f32_e32 v0, v0
	v_pk_add_f32 v[152:153], v[152:153], 1.0 op_sel_hi:[1,0]
	v_pk_mul_f32 v[36:37], v[36:37], v[134:135]
	v_add_f32_e32 v0, 1.0, v0
	v_rcp_f32_e32 v137, v0
	s_nop 0
	v_pk_mul_f32 v[136:137], v[152:153], v[136:137]
	s_nop 0
	v_pk_mul_f32 v[38:39], v[38:39], v[136:137]
	s_nop 0
	s_nop 0
	s_nop 0
	s_waitcnt vmcnt(0)
	v_mov_b32_e32 v132, v204
	v_mov_b32_e32 v133, v205
	v_mov_b32_e32 v134, v206
	v_mov_b32_e32 v135, v207
	v_mov_b32_e32 v136, v208
	v_mov_b32_e32 v137, v209
	v_mov_b32_e32 v138, v210
	v_mov_b32_e32 v139, v211
	v_lshlrev_b32_e32 v0, 16, v136
	v_mul_f32_e32 v0, 0xbfb8aa3b, v0
	v_exp_f32_e32 v2, v0
	v_lshlrev_b32_e32 v0, 16, v132
	v_mul_f32_e32 v0, 0xbfb8aa3b, v0
	v_exp_f32_e32 v0, v0
	s_nop 0
	v_add_f32_e32 v0, 1.0, v0
	v_rcp_f32_e32 v152, v0
	v_and_b32_e32 v0, 0xffff0000, v136
	v_mul_f32_e32 v0, 0xbfb8aa3b, v0
	v_exp_f32_e32 v3, v0
	v_and_b32_e32 v0, 0xffff0000, v132
	v_mul_f32_e32 v0, 0xbfb8aa3b, v0
	v_exp_f32_e32 v0, v0
	v_pk_add_f32 v[2:3], v[2:3], 1.0 op_sel_hi:[1,0]
	v_add_f32_e32 v0, 1.0, v0
	v_rcp_f32_e32 v153, v0
	v_lshlrev_b32_e32 v0, 16, v137
	v_mul_f32_e32 v0, 0xbfb8aa3b, v0
	v_exp_f32_e32 v136, v0
	v_lshlrev_b32_e32 v0, 16, v133
	v_mul_f32_e32 v0, 0xbfb8aa3b, v0
	v_exp_f32_e32 v0, v0
	v_pk_mul_f32 v[2:3], v[2:3], v[152:153]
	v_add_f32_e32 v0, 1.0, v0
	v_rcp_f32_e32 v132, v0
	v_and_b32_e32 v0, 0xffff0000, v137
	v_mul_f32_e32 v0, 0xbfb8aa3b, v0
	v_exp_f32_e32 v137, v0
	v_and_b32_e32 v0, 0xffff0000, v133
	v_mul_f32_e32 v0, 0xbfb8aa3b, v0
	v_exp_f32_e32 v0, v0
	v_pk_mul_f32 v[8:9], v[8:9], v[2:3]
	v_pk_add_f32 v[136:137], v[136:137], 1.0 op_sel_hi:[1,0]
	v_add_f32_e32 v0, 1.0, v0
	v_rcp_f32_e32 v133, v0
	v_lshlrev_b32_e32 v0, 16, v138
	v_mul_f32_e32 v0, 0xbfb8aa3b, v0
	v_exp_f32_e32 v2, v0
	v_lshlrev_b32_e32 v0, 16, v134
	v_mul_f32_e32 v0, 0xbfb8aa3b, v0
	v_exp_f32_e32 v0, v0
	v_pk_mul_f32 v[132:133], v[136:137], v[132:133]
	v_add_f32_e32 v0, 1.0, v0
	v_pk_mul_f32 v[10:11], v[10:11], v[132:133]
	v_rcp_f32_e32 v132, v0
	v_and_b32_e32 v0, 0xffff0000, v138
	v_mul_f32_e32 v0, 0xbfb8aa3b, v0
	v_exp_f32_e32 v3, v0
	v_and_b32_e32 v0, 0xffff0000, v134
	v_mul_f32_e32 v0, 0xbfb8aa3b, v0
	v_exp_f32_e32 v0, v0
	v_pk_add_f32 v[2:3], v[2:3], 1.0 op_sel_hi:[1,0]
	v_add_f32_e32 v0, 1.0, v0
	v_rcp_f32_e32 v133, v0
	v_lshlrev_b32_e32 v0, 16, v139
	v_mul_f32_e32 v0, 0xbfb8aa3b, v0
	v_exp_f32_e32 v136, v0
	v_lshlrev_b32_e32 v0, 16, v135
	v_mul_f32_e32 v0, 0xbfb8aa3b, v0
	v_exp_f32_e32 v0, v0
	v_pk_mul_f32 v[2:3], v[2:3], v[132:133]
	v_add_f32_e32 v0, 1.0, v0
	v_rcp_f32_e32 v134, v0
	v_and_b32_e32 v0, 0xffff0000, v139
	v_mul_f32_e32 v0, 0xbfb8aa3b, v0
	v_exp_f32_e32 v137, v0
	v_and_b32_e32 v0, 0xffff0000, v135
	v_mul_f32_e32 v0, 0xbfb8aa3b, v0
	v_exp_f32_e32 v0, v0
	v_pk_add_f32 v[136:137], v[136:137], 1.0 op_sel_hi:[1,0]
	v_pk_mul_f32 v[4:5], v[4:5], v[2:3]
	v_add_f32_e32 v0, 1.0, v0
	v_rcp_f32_e32 v135, v0
	s_nop 0
	v_pk_mul_f32 v[132:133], v[136:137], v[134:135]
	s_nop 0
	v_pk_mul_f32 v[6:7], v[6:7], v[132:133]
